# v20 + same LDS-DMA prefetch of epilogue fold vectors (and HGRN lower bounds) for the HGRN in-proj and gMLP in-proj GEMMs; 3 KB extra static LDS
# baseline (speedup 1.0000x reference)
.LBB0_211:
	s_add_i32 s60, s60, 1
	s_mov_b64 s[36:37], s[18:19]
	s_mul_i32 s18, s60, s26
	s_add_i32 s38, s18, s2
	s_cmpk_gt_i32 s38, 0x1ff
	s_cselect_b64 s[44:45], -1, 0
	s_lshl_b32 s18, s38, 3
	s_and_b32 s18, s18, 56
	s_bfe_u32 s19, s38, 0x30003
	s_mov_b32 s27, s61
	s_or_b32 s61, s18, s19
	s_mov_b32 s3, s42
	s_ashr_i32 s42, s38, 6
	s_lshl_b32 s18, s61, 19
	s_mov_b64 s[4:5], s[20:21]
	s_add_u32 s20, s14, s18
	s_addc_u32 s21, s15, 0
	s_ashr_i32 s43, s42, 31
	s_lshl_b64 s[18:19], s[42:43], 19
	s_add_u32 s18, s16, s18
	s_addc_u32 s19, s17, s19
	s_cmpk_lt_i32 s38, 0x200
	s_cselect_b32 s38, s21, s5
	s_cselect_b32 s43, s20, s4
	s_cselect_b32 s62, s19, s37
	s_cselect_b32 s63, s18, s36
	s_add_u32 s64, s36, 0x100
	s_addc_u32 s65, s37, 0
	s_mov_b32 s66, -2
	s_waitcnt lgkmcnt(0)
	s_add_u32 s36, s4, 0x100
	s_addc_u32 s37, s5, 0
	s_add_i32 s67, 0, 0x10000
	v_add_u32_e32 v1, s67, v191
	ds_read_b128 v[34:37], v1
	ds_read_b128 v[38:41], v1 offset:1024
	ds_read_b128 v[42:45], v1 offset:2048
	ds_read_b128 v[46:49], v1 offset:3072
	s_cmp_eq_u32 s66, 12
	s_cselect_b32 s49, s38, s37
	s_cselect_b32 s48, s43, s36
	s_cselect_b32 s47, s62, s65
	s_cselect_b32 s46, s63, s64
	v_lshl_add_u64 v[186:187], s[4:5], 0, v[168:169]
	s_add_i32 m0, s53, 0xc000
	ds_read_b128 v[50:53], v206
	ds_read_b128 v[58:61], v206 offset:1024
	ds_read_b128 v[62:65], v206 offset:2048
	ds_read_b128 v[66:69], v206 offset:3072
	ds_read_b128 v[170:173], v206 offset:4096
	ds_read_b128 v[174:177], v206 offset:5120
	ds_read_b128 v[178:181], v206 offset:6144
	ds_read_b128 v[182:185], v206 offset:7168
	global_load_lds_dwordx4 v[186:187], off
	v_lshl_add_u64 v[186:187], s[4:5], 0, v[166:167]
	s_add_i32 m0, s53, 0xe000
	s_nop 0
	global_load_lds_dwordx4 v[186:187], off
	s_waitcnt lgkmcnt(8)
	s_barrier
	s_waitcnt lgkmcnt(0)
	s_setprio 1
	s_waitcnt lgkmcnt(0)
	v_mfma_f32_16x16x32_bf16 v[158:161], v[34:37], v[50:53], 0
	v_mfma_f32_16x16x32_bf16 v[154:157], v[42:45], v[50:53], 0
	v_mfma_f32_16x16x32_bf16 v[142:145], v[34:37], v[62:65], 0
	v_mfma_f32_16x16x32_bf16 v[138:141], v[42:45], v[62:65], 0
	v_mfma_f32_16x16x32_bf16 v[126:129], v[34:37], v[170:173], 0
	v_mfma_f32_16x16x32_bf16 v[122:125], v[42:45], v[170:173], 0
	v_mfma_f32_16x16x32_bf16 v[110:113], v[34:37], v[178:181], 0
	v_mfma_f32_16x16x32_bf16 v[106:109], v[42:45], v[178:181], 0
	v_mfma_f32_16x16x32_bf16 v[158:161], v[38:41], v[58:61], v[158:161]
	v_mfma_f32_16x16x32_bf16 v[154:157], v[46:49], v[58:61], v[154:157]
	v_mfma_f32_16x16x32_bf16 v[142:145], v[38:41], v[66:69], v[142:145]
	v_mfma_f32_16x16x32_bf16 v[138:141], v[46:49], v[66:69], v[138:141]
	v_mfma_f32_16x16x32_bf16 v[126:129], v[38:41], v[174:177], v[126:129]
	v_mfma_f32_16x16x32_bf16 v[122:125], v[46:49], v[174:177], v[122:125]
	v_mfma_f32_16x16x32_bf16 v[110:113], v[38:41], v[182:185], v[110:113]
	v_mfma_f32_16x16x32_bf16 v[106:109], v[46:49], v[182:185], v[106:109]
	s_setprio 0
	s_barrier
	v_mbcnt_lo_u32_b32 v250, -1, 0
	v_mbcnt_hi_u32_b32 v250, -1, v250
	v_lshlrev_b32_e32 v250, 4, v250
	s_lshl_b32 s32, s3, 10
	s_add_u32 s90, s8, s32
	s_addc_u32 s91, s9, 0
	s_add_u32 s92, s10, s32
	s_addc_u32 s93, s11, 0
	s_mov_b32 m0, 0x20840
	s_nop 0
	global_load_lds_dwordx4 v250, s[90:91]
	s_mov_b32 m0, 0x20c40
	s_nop 0
	global_load_lds_dwordx4 v250, s[92:93]
	s_add_i32 s68, 0, 0x14000
	s_add_i32 s4, s67, s52
	v_add_u32_e32 v1, s68, v191
	v_lshl_add_u64 v[214:215], s[46:47], 0, v[164:165]
	s_mov_b32 m0, s4
	ds_read_b128 v[186:189], v1
	ds_read_b128 v[208:211], v1 offset:1024
	ds_read_b128 v[222:225], v1 offset:2048
	ds_read_b128 v[226:229], v1 offset:3072
	global_load_lds_dwordx4 v[214:215], off
	v_lshl_add_u64 v[238:239], s[46:47], 0, v[162:163]
	s_add_i32 m0, s4, 0x2000
	s_nop 0
	global_load_lds_dwordx4 v[238:239], off
	s_barrier
	s_waitcnt lgkmcnt(0)
	s_setprio 1
	s_waitcnt lgkmcnt(0)
	v_mfma_f32_16x16x32_bf16 v[150:153], v[186:189], v[50:53], 0
	v_mfma_f32_16x16x32_bf16 v[50:53], v[222:225], v[50:53], 0
	v_mfma_f32_16x16x32_bf16 v[150:153], v[208:211], v[58:61], v[150:153]
	v_mfma_f32_16x16x32_bf16 v[50:53], v[226:229], v[58:61], v[50:53]
	v_mfma_f32_16x16x32_bf16 v[58:61], v[186:189], v[62:65], 0
	v_mfma_f32_16x16x32_bf16 v[62:65], v[222:225], v[62:65], 0
	v_mfma_f32_16x16x32_bf16 v[114:117], v[222:225], v[170:173], 0
	v_mfma_f32_16x16x32_bf16 v[102:105], v[186:189], v[178:181], 0
	v_mfma_f32_16x16x32_bf16 v[98:101], v[222:225], v[178:181], 0
	v_mfma_f32_16x16x32_bf16 v[58:61], v[208:211], v[66:69], v[58:61]
	v_mfma_f32_16x16x32_bf16 v[62:65], v[226:229], v[66:69], v[62:65]
	v_mfma_f32_16x16x32_bf16 v[66:69], v[186:189], v[170:173], 0
	v_mfma_f32_16x16x32_bf16 v[114:117], v[226:229], v[174:177], v[114:117]
	v_mfma_f32_16x16x32_bf16 v[102:105], v[208:211], v[182:185], v[102:105]
	v_mfma_f32_16x16x32_bf16 v[98:101], v[226:229], v[182:185], v[98:101]
	v_mfma_f32_16x16x32_bf16 v[66:69], v[208:211], v[174:177], v[66:69]
	s_setprio 0
	s_mov_b32 m0, s53
	v_lshl_add_u64 v[240:241], s[48:49], 0, v[164:165]
	s_barrier
	ds_read_b128 v[118:121], v206 offset:16384
	ds_read_b128 v[130:133], v206 offset:17408
	ds_read_b128 v[134:137], v206 offset:18432
	ds_read_b128 v[146:149], v206 offset:19456
	ds_read_b128 v[170:173], v206 offset:20480
	ds_read_b128 v[174:177], v206 offset:21504
	ds_read_b128 v[178:181], v206 offset:22528
	ds_read_b128 v[182:185], v206 offset:23552
	global_load_lds_dwordx4 v[240:241], off
	v_lshl_add_u64 v[242:243], s[48:49], 0, v[162:163]
	s_mov_b32 m0, s54
	s_nop 0
	global_load_lds_dwordx4 v[242:243], off
	s_barrier
	s_waitcnt lgkmcnt(0)
	s_setprio 1
	s_waitcnt lgkmcnt(0)
	v_mfma_f32_16x16x32_bf16 v[94:97], v[34:37], v[118:121], 0
	v_mfma_f32_16x16x32_bf16 v[90:93], v[42:45], v[118:121], 0
	v_mfma_f32_16x16x32_bf16 v[78:81], v[34:37], v[134:137], 0
	v_mfma_f32_16x16x32_bf16 v[74:77], v[42:45], v[134:137], 0
	v_mfma_f32_16x16x32_bf16 v[30:33], v[34:37], v[170:173], 0
	v_mfma_f32_16x16x32_bf16 v[26:29], v[42:45], v[170:173], 0
	v_mfma_f32_16x16x32_bf16 v[14:17], v[34:37], v[178:181], 0
	v_mfma_f32_16x16x32_bf16 v[10:13], v[42:45], v[178:181], 0
	v_mfma_f32_16x16x32_bf16 v[94:97], v[38:41], v[130:133], v[94:97]
	v_mfma_f32_16x16x32_bf16 v[90:93], v[46:49], v[130:133], v[90:93]
	v_mfma_f32_16x16x32_bf16 v[78:81], v[38:41], v[146:149], v[78:81]
	v_mfma_f32_16x16x32_bf16 v[74:77], v[46:49], v[146:149], v[74:77]
	v_mfma_f32_16x16x32_bf16 v[30:33], v[38:41], v[174:177], v[30:33]
	v_mfma_f32_16x16x32_bf16 v[26:29], v[46:49], v[174:177], v[26:29]
	v_mfma_f32_16x16x32_bf16 v[14:17], v[38:41], v[182:185], v[14:17]
	v_mfma_f32_16x16x32_bf16 v[10:13], v[46:49], v[182:185], v[10:13]
	s_setprio 0
	s_barrier
	s_add_u32 s4, s46, 0x40000
	s_addc_u32 s5, s47, 0
	s_add_i32 s67, s68, s52
	v_lshl_add_u64 v[34:35], s[4:5], 0, v[164:165]
	s_mov_b32 m0, s67
	s_nop 0
	global_load_lds_dwordx4 v[34:35], off
	v_lshl_add_u64 v[34:35], s[4:5], 0, v[162:163]
	s_add_i32 m0, s67, 0x2000
	s_nop 0
	global_load_lds_dwordx4 v[34:35], off
	s_waitcnt vmcnt(6)
	s_barrier
	s_setprio 1
	v_mfma_f32_16x16x32_bf16 v[22:25], v[186:189], v[170:173], 0
	v_mfma_f32_16x16x32_bf16 v[18:21], v[222:225], v[170:173], 0
	v_mfma_f32_16x16x32_bf16 v[6:9], v[186:189], v[178:181], 0
	v_mfma_f32_16x16x32_bf16 v[2:5], v[222:225], v[178:181], 0
	v_mfma_f32_16x16x32_bf16 v[34:37], v[186:189], v[118:121], 0
	v_mfma_f32_16x16x32_bf16 v[38:41], v[222:225], v[118:121], 0
	v_mfma_f32_16x16x32_bf16 v[42:45], v[186:189], v[134:137], 0
	v_mfma_f32_16x16x32_bf16 v[46:49], v[222:225], v[134:137], 0
	v_mfma_f32_16x16x32_bf16 v[22:25], v[208:211], v[174:177], v[22:25]
	v_mfma_f32_16x16x32_bf16 v[18:21], v[226:229], v[174:177], v[18:21]
	v_mfma_f32_16x16x32_bf16 v[6:9], v[208:211], v[182:185], v[6:9]
	v_mfma_f32_16x16x32_bf16 v[2:5], v[226:229], v[182:185], v[2:5]
	v_mfma_f32_16x16x32_bf16 v[34:37], v[208:211], v[130:133], v[34:37]
	v_mfma_f32_16x16x32_bf16 v[38:41], v[226:229], v[130:133], v[38:41]
	v_mfma_f32_16x16x32_bf16 v[42:45], v[208:211], v[146:149], v[42:45]
	v_mfma_f32_16x16x32_bf16 v[46:49], v[226:229], v[146:149], v[46:49]
	s_setprio 0
	s_add_i32 s67, 0, 0x18000
	v_add_u32_e32 v1, s67, v191
	s_barrier
	ds_read_b128 v[54:57], v1
	ds_read_b128 v[70:73], v1 offset:1024
	ds_read_b128 v[82:85], v1 offset:2048
	ds_read_b128 v[86:89], v1 offset:3072
	s_add_u32 s4, s48, 0x40000
	s_addc_u32 s5, s49, 0
	s_mov_b32 m0, s55
	v_lshl_add_u64 v[134:135], s[4:5], 0, v[164:165]
	ds_read_b128 v[118:121], v206 offset:32768
	ds_read_b128 v[130:133], v206 offset:33792
	ds_read_b128 v[170:173], v206 offset:34816
	ds_read_b128 v[174:177], v206 offset:35840
	ds_read_b128 v[178:181], v206 offset:36864
	ds_read_b128 v[182:185], v206 offset:37888
	ds_read_b128 v[186:189], v206 offset:38912
	ds_read_b128 v[208:211], v206 offset:39936
	global_load_lds_dwordx4 v[134:135], off
	v_lshl_add_u64 v[134:135], s[4:5], 0, v[162:163]
	s_mov_b32 m0, s56
	s_nop 0
	global_load_lds_dwordx4 v[134:135], off
	s_waitcnt lgkmcnt(8)
	s_barrier
	s_waitcnt lgkmcnt(0)
	s_setprio 1
	s_waitcnt lgkmcnt(0)
	v_mfma_f32_16x16x32_bf16 v[134:137], v[54:57], v[118:121], v[158:161]
	v_mfma_f32_16x16x32_bf16 v[158:161], v[70:73], v[130:133], v[134:137]
	v_mfma_f32_16x16x32_bf16 v[134:137], v[82:85], v[118:121], v[154:157]
	v_mfma_f32_16x16x32_bf16 v[154:157], v[86:89], v[130:133], v[134:137]
	v_mfma_f32_16x16x32_bf16 v[134:137], v[54:57], v[170:173], v[142:145]
	v_mfma_f32_16x16x32_bf16 v[142:145], v[70:73], v[174:177], v[134:137]
	v_mfma_f32_16x16x32_bf16 v[134:137], v[82:85], v[170:173], v[138:141]
	v_mfma_f32_16x16x32_bf16 v[126:129], v[54:57], v[178:181], v[126:129]
	v_mfma_f32_16x16x32_bf16 v[122:125], v[82:85], v[178:181], v[122:125]
	v_mfma_f32_16x16x32_bf16 v[110:113], v[54:57], v[186:189], v[110:113]
	v_mfma_f32_16x16x32_bf16 v[106:109], v[82:85], v[186:189], v[106:109]
	v_mfma_f32_16x16x32_bf16 v[138:141], v[86:89], v[174:177], v[134:137]
	v_mfma_f32_16x16x32_bf16 v[126:129], v[70:73], v[182:185], v[126:129]
	v_mfma_f32_16x16x32_bf16 v[122:125], v[86:89], v[182:185], v[122:125]
	v_mfma_f32_16x16x32_bf16 v[110:113], v[70:73], v[208:211], v[110:113]
	v_mfma_f32_16x16x32_bf16 v[106:109], v[86:89], v[208:211], v[106:109]
	s_setprio 0
	s_barrier
	s_add_i32 s48, 0, 0x1c000
	s_add_i32 s4, s67, s52
	v_add_u32_e32 v1, s48, v191
	v_lshl_add_u64 v[134:135], v[214:215], 0, s[22:23]
	s_mov_b32 m0, s4
	ds_read_b128 v[222:225], v1
	ds_read_b128 v[226:229], v1 offset:1024
	ds_read_b128 v[230:233], v1 offset:2048
	ds_read_b128 v[234:237], v1 offset:3072
	global_load_lds_dwordx4 v[134:135], off
	v_lshl_add_u64 v[134:135], v[238:239], 0, s[22:23]
	s_add_i32 m0, s4, 0x2000
	s_nop 0
	global_load_lds_dwordx4 v[134:135], off
	s_barrier
	s_waitcnt lgkmcnt(0)
	s_setprio 1
	s_waitcnt lgkmcnt(0)
	v_mfma_f32_16x16x32_bf16 v[50:53], v[230:233], v[118:121], v[50:53]
	v_mfma_f32_16x16x32_bf16 v[134:137], v[222:225], v[118:121], v[150:153]
	v_mfma_f32_16x16x32_bf16 v[146:149], v[234:237], v[130:133], v[50:53]
	v_mfma_f32_16x16x32_bf16 v[50:53], v[222:225], v[170:173], v[58:61]
	v_mfma_f32_16x16x32_bf16 v[150:153], v[226:229], v[130:133], v[134:137]
	v_mfma_f32_16x16x32_bf16 v[134:137], v[226:229], v[174:177], v[50:53]
	v_mfma_f32_16x16x32_bf16 v[50:53], v[230:233], v[170:173], v[62:65]
	v_mfma_f32_16x16x32_bf16 v[130:133], v[234:237], v[174:177], v[50:53]
	v_mfma_f32_16x16x32_bf16 v[50:53], v[222:225], v[178:181], v[66:69]
	v_mfma_f32_16x16x32_bf16 v[118:121], v[226:229], v[182:185], v[50:53]
	v_mfma_f32_16x16x32_bf16 v[50:53], v[230:233], v[178:181], v[114:117]
	v_mfma_f32_16x16x32_bf16 v[114:117], v[234:237], v[182:185], v[50:53]
	v_mfma_f32_16x16x32_bf16 v[50:53], v[222:225], v[186:189], v[102:105]
	v_mfma_f32_16x16x32_bf16 v[102:105], v[226:229], v[208:211], v[50:53]
	v_mfma_f32_16x16x32_bf16 v[50:53], v[230:233], v[186:189], v[98:101]
	v_mfma_f32_16x16x32_bf16 v[98:101], v[234:237], v[208:211], v[50:53]
	s_setprio 0
	s_mov_b32 m0, s58
	v_lshl_add_u64 v[186:187], v[240:241], 0, s[22:23]
	s_barrier
	s_nop 2
	ds_read_b128 v[50:53], v206 offset:49152
	ds_read_b128 v[58:61], v206 offset:50176
	ds_read_b128 v[62:65], v206 offset:51200
	ds_read_b128 v[66:69], v206 offset:52224
	ds_read_b128 v[170:173], v206 offset:53248
	ds_read_b128 v[174:177], v206 offset:54272
	ds_read_b128 v[178:181], v206 offset:55296
	ds_read_b128 v[182:185], v206 offset:56320
	global_load_lds_dwordx4 v[186:187], off
	v_lshl_add_u64 v[186:187], v[242:243], 0, s[22:23]
	s_mov_b32 m0, s59
	s_nop 0
	global_load_lds_dwordx4 v[186:187], off
	s_barrier
	s_waitcnt lgkmcnt(0)
	s_setprio 1
	s_waitcnt lgkmcnt(0)
	v_mfma_f32_16x16x32_bf16 v[94:97], v[54:57], v[50:53], v[94:97]
	v_mfma_f32_16x16x32_bf16 v[90:93], v[82:85], v[50:53], v[90:93]
	v_mfma_f32_16x16x32_bf16 v[78:81], v[54:57], v[62:65], v[78:81]
	v_mfma_f32_16x16x32_bf16 v[74:77], v[82:85], v[62:65], v[74:77]
	v_mfma_f32_16x16x32_bf16 v[30:33], v[54:57], v[170:173], v[30:33]
	v_mfma_f32_16x16x32_bf16 v[26:29], v[82:85], v[170:173], v[26:29]
	v_mfma_f32_16x16x32_bf16 v[14:17], v[54:57], v[178:181], v[14:17]
	v_mfma_f32_16x16x32_bf16 v[10:13], v[82:85], v[178:181], v[10:13]
	v_mfma_f32_16x16x32_bf16 v[94:97], v[70:73], v[58:61], v[94:97]
	v_mfma_f32_16x16x32_bf16 v[90:93], v[86:89], v[58:61], v[90:93]
	v_mfma_f32_16x16x32_bf16 v[78:81], v[70:73], v[66:69], v[78:81]
	v_mfma_f32_16x16x32_bf16 v[74:77], v[86:89], v[66:69], v[74:77]
	v_mfma_f32_16x16x32_bf16 v[30:33], v[70:73], v[174:177], v[30:33]
	v_mfma_f32_16x16x32_bf16 v[26:29], v[86:89], v[174:177], v[26:29]
	v_mfma_f32_16x16x32_bf16 v[14:17], v[70:73], v[182:185], v[14:17]
	v_mfma_f32_16x16x32_bf16 v[10:13], v[86:89], v[182:185], v[10:13]
	s_setprio 0
	s_barrier
	s_add_u32 s4, s46, 0x40080
	s_addc_u32 s5, s47, 0
	s_add_i32 s46, s48, s52
	v_lshl_add_u64 v[54:55], s[4:5], 0, v[164:165]
	s_mov_b32 m0, s46
	s_nop 0
	global_load_lds_dwordx4 v[54:55], off
	v_lshl_add_u64 v[54:55], s[4:5], 0, v[162:163]
	s_add_i32 m0, s46, 0x2000
	s_nop 0
	global_load_lds_dwordx4 v[54:55], off
	s_waitcnt vmcnt(6)
	s_barrier
	s_setprio 1
	v_mfma_f32_16x16x32_bf16 v[34:37], v[222:225], v[50:53], v[34:37]
	v_mfma_f32_16x16x32_bf16 v[86:89], v[226:229], v[58:61], v[34:37]
	v_mfma_f32_16x16x32_bf16 v[34:37], v[230:233], v[50:53], v[38:41]
	v_mfma_f32_16x16x32_bf16 v[82:85], v[234:237], v[58:61], v[34:37]
	v_mfma_f32_16x16x32_bf16 v[34:37], v[222:225], v[62:65], v[42:45]
	v_mfma_f32_16x16x32_bf16 v[70:73], v[226:229], v[66:69], v[34:37]
	v_mfma_f32_16x16x32_bf16 v[34:37], v[230:233], v[62:65], v[46:49]
	v_mfma_f32_16x16x32_bf16 v[22:25], v[222:225], v[170:173], v[22:25]
	v_mfma_f32_16x16x32_bf16 v[18:21], v[230:233], v[170:173], v[18:21]
	v_mfma_f32_16x16x32_bf16 v[6:9], v[222:225], v[178:181], v[6:9]
	v_mfma_f32_16x16x32_bf16 v[2:5], v[230:233], v[178:181], v[2:5]
	v_mfma_f32_16x16x32_bf16 v[54:57], v[234:237], v[66:69], v[34:37]
	v_mfma_f32_16x16x32_bf16 v[22:25], v[226:229], v[174:177], v[22:25]
	v_mfma_f32_16x16x32_bf16 v[18:21], v[234:237], v[174:177], v[18:21]
	v_mfma_f32_16x16x32_bf16 v[6:9], v[226:229], v[182:185], v[6:9]
	v_mfma_f32_16x16x32_bf16 v[2:5], v[234:237], v[182:185], v[2:5]
	s_setprio 0
	s_add_i32 s66, s66, 2
	s_add_u32 s64, s64, 0x100
	s_addc_u32 s65, s65, 0
	s_cmp_gt_u32 s66, 13
	s_mov_b64 s[4:5], s[36:37]
	s_barrier
.LBB0_212:
	s_add_u32 s36, s4, 0x100
	s_addc_u32 s37, s5, 0
	s_add_i32 s67, 0, 0x10000
	v_add_u32_e32 v1, s67, v191
	ds_read_b128 v[34:37], v1
	ds_read_b128 v[38:41], v1 offset:1024
	ds_read_b128 v[42:45], v1 offset:2048
	ds_read_b128 v[46:49], v1 offset:3072
	s_cmp_eq_u32 s66, 12
	s_cselect_b32 s49, s38, s37
	s_cselect_b32 s48, s43, s36
	s_cselect_b32 s47, s62, s65
	s_cselect_b32 s46, s63, s64
	v_lshl_add_u64 v[186:187], s[4:5], 0, v[168:169]
	s_add_i32 m0, s53, 0xc000
	ds_read_b128 v[50:53], v206
	ds_read_b128 v[58:61], v206 offset:1024
	ds_read_b128 v[62:65], v206 offset:2048
	ds_read_b128 v[66:69], v206 offset:3072
	ds_read_b128 v[170:173], v206 offset:4096
	ds_read_b128 v[174:177], v206 offset:5120
	ds_read_b128 v[178:181], v206 offset:6144
	ds_read_b128 v[182:185], v206 offset:7168
	global_load_lds_dwordx4 v[186:187], off
	v_lshl_add_u64 v[186:187], s[4:5], 0, v[166:167]
	s_add_i32 m0, s53, 0xe000
	s_nop 0
	global_load_lds_dwordx4 v[186:187], off
	s_waitcnt lgkmcnt(8)
	s_barrier
	s_waitcnt lgkmcnt(0)
	s_setprio 1
	s_waitcnt lgkmcnt(0)
	v_mfma_f32_16x16x32_bf16 v[158:161], v[34:37], v[50:53], v[158:161]
	v_mfma_f32_16x16x32_bf16 v[154:157], v[42:45], v[50:53], v[154:157]
	v_mfma_f32_16x16x32_bf16 v[142:145], v[34:37], v[62:65], v[142:145]
	v_mfma_f32_16x16x32_bf16 v[138:141], v[42:45], v[62:65], v[138:141]
	v_mfma_f32_16x16x32_bf16 v[126:129], v[34:37], v[170:173], v[126:129]
	v_mfma_f32_16x16x32_bf16 v[122:125], v[42:45], v[170:173], v[122:125]
	v_mfma_f32_16x16x32_bf16 v[110:113], v[34:37], v[178:181], v[110:113]
	v_mfma_f32_16x16x32_bf16 v[106:109], v[42:45], v[178:181], v[106:109]
	v_mfma_f32_16x16x32_bf16 v[158:161], v[38:41], v[58:61], v[158:161]
	v_mfma_f32_16x16x32_bf16 v[154:157], v[46:49], v[58:61], v[154:157]
	v_mfma_f32_16x16x32_bf16 v[142:145], v[38:41], v[66:69], v[142:145]
	v_mfma_f32_16x16x32_bf16 v[138:141], v[46:49], v[66:69], v[138:141]
	v_mfma_f32_16x16x32_bf16 v[126:129], v[38:41], v[174:177], v[126:129]
	v_mfma_f32_16x16x32_bf16 v[122:125], v[46:49], v[174:177], v[122:125]
	v_mfma_f32_16x16x32_bf16 v[110:113], v[38:41], v[182:185], v[110:113]
	v_mfma_f32_16x16x32_bf16 v[106:109], v[46:49], v[182:185], v[106:109]
	s_setprio 0
	s_barrier
	s_add_i32 s68, 0, 0x14000
	s_add_i32 s4, s67, s52
	v_add_u32_e32 v1, s68, v191
	v_lshl_add_u64 v[214:215], s[46:47], 0, v[164:165]
	s_mov_b32 m0, s4
	ds_read_b128 v[186:189], v1
	ds_read_b128 v[208:211], v1 offset:1024
	ds_read_b128 v[222:225], v1 offset:2048
	ds_read_b128 v[226:229], v1 offset:3072
	global_load_lds_dwordx4 v[214:215], off
	v_lshl_add_u64 v[238:239], s[46:47], 0, v[162:163]
	s_add_i32 m0, s4, 0x2000
	s_nop 0
	global_load_lds_dwordx4 v[238:239], off
	s_barrier
	s_waitcnt lgkmcnt(0)
	s_setprio 1
	s_waitcnt lgkmcnt(0)
	v_mfma_f32_16x16x32_bf16 v[150:153], v[186:189], v[50:53], v[150:153]
	v_mfma_f32_16x16x32_bf16 v[50:53], v[222:225], v[50:53], v[146:149]
	v_mfma_f32_16x16x32_bf16 v[150:153], v[208:211], v[58:61], v[150:153]
	v_mfma_f32_16x16x32_bf16 v[50:53], v[226:229], v[58:61], v[50:53]
	v_mfma_f32_16x16x32_bf16 v[58:61], v[186:189], v[62:65], v[134:137]
	v_mfma_f32_16x16x32_bf16 v[62:65], v[222:225], v[62:65], v[130:133]
	v_mfma_f32_16x16x32_bf16 v[114:117], v[222:225], v[170:173], v[114:117]
	v_mfma_f32_16x16x32_bf16 v[102:105], v[186:189], v[178:181], v[102:105]
	v_mfma_f32_16x16x32_bf16 v[98:101], v[222:225], v[178:181], v[98:101]
	v_mfma_f32_16x16x32_bf16 v[58:61], v[208:211], v[66:69], v[58:61]
	v_mfma_f32_16x16x32_bf16 v[62:65], v[226:229], v[66:69], v[62:65]
	v_mfma_f32_16x16x32_bf16 v[66:69], v[186:189], v[170:173], v[118:121]
	v_mfma_f32_16x16x32_bf16 v[114:117], v[226:229], v[174:177], v[114:117]
	v_mfma_f32_16x16x32_bf16 v[102:105], v[208:211], v[182:185], v[102:105]
	v_mfma_f32_16x16x32_bf16 v[98:101], v[226:229], v[182:185], v[98:101]
	v_mfma_f32_16x16x32_bf16 v[66:69], v[208:211], v[174:177], v[66:69]
	s_setprio 0
	s_mov_b32 m0, s53
	v_lshl_add_u64 v[240:241], s[48:49], 0, v[164:165]
	s_barrier
	ds_read_b128 v[118:121], v206 offset:16384
	ds_read_b128 v[130:133], v206 offset:17408
	ds_read_b128 v[134:137], v206 offset:18432
	ds_read_b128 v[146:149], v206 offset:19456
	ds_read_b128 v[170:173], v206 offset:20480
	ds_read_b128 v[174:177], v206 offset:21504
	ds_read_b128 v[178:181], v206 offset:22528
	ds_read_b128 v[182:185], v206 offset:23552
	global_load_lds_dwordx4 v[240:241], off
	v_lshl_add_u64 v[242:243], s[48:49], 0, v[162:163]
	s_mov_b32 m0, s54
	s_nop 0
	global_load_lds_dwordx4 v[242:243], off
	s_barrier
	s_waitcnt lgkmcnt(0)
	s_setprio 1
	s_waitcnt lgkmcnt(0)
	v_mfma_f32_16x16x32_bf16 v[94:97], v[34:37], v[118:121], v[94:97]
	v_mfma_f32_16x16x32_bf16 v[90:93], v[42:45], v[118:121], v[90:93]
	v_mfma_f32_16x16x32_bf16 v[78:81], v[34:37], v[134:137], v[78:81]
	v_mfma_f32_16x16x32_bf16 v[74:77], v[42:45], v[134:137], v[74:77]
	v_mfma_f32_16x16x32_bf16 v[30:33], v[34:37], v[170:173], v[30:33]
	v_mfma_f32_16x16x32_bf16 v[26:29], v[42:45], v[170:173], v[26:29]
	v_mfma_f32_16x16x32_bf16 v[14:17], v[34:37], v[178:181], v[14:17]
	v_mfma_f32_16x16x32_bf16 v[10:13], v[42:45], v[178:181], v[10:13]
	v_mfma_f32_16x16x32_bf16 v[94:97], v[38:41], v[130:133], v[94:97]
	v_mfma_f32_16x16x32_bf16 v[90:93], v[46:49], v[130:133], v[90:93]
	v_mfma_f32_16x16x32_bf16 v[78:81], v[38:41], v[146:149], v[78:81]
	v_mfma_f32_16x16x32_bf16 v[74:77], v[46:49], v[146:149], v[74:77]
	v_mfma_f32_16x16x32_bf16 v[30:33], v[38:41], v[174:177], v[30:33]
	v_mfma_f32_16x16x32_bf16 v[26:29], v[46:49], v[174:177], v[26:29]
	v_mfma_f32_16x16x32_bf16 v[14:17], v[38:41], v[182:185], v[14:17]
	v_mfma_f32_16x16x32_bf16 v[10:13], v[46:49], v[182:185], v[10:13]
	s_setprio 0
	s_barrier
	s_add_u32 s4, s46, 0x40000
	s_addc_u32 s5, s47, 0
	s_add_i32 s67, s68, s52
	v_lshl_add_u64 v[34:35], s[4:5], 0, v[164:165]
	s_mov_b32 m0, s67
	s_nop 0
	global_load_lds_dwordx4 v[34:35], off
	v_lshl_add_u64 v[34:35], s[4:5], 0, v[162:163]
	s_add_i32 m0, s67, 0x2000
	s_nop 0
	global_load_lds_dwordx4 v[34:35], off
	s_waitcnt vmcnt(6)
	s_barrier
	s_setprio 1
	v_mfma_f32_16x16x32_bf16 v[22:25], v[186:189], v[170:173], v[22:25]
	v_mfma_f32_16x16x32_bf16 v[18:21], v[222:225], v[170:173], v[18:21]
	v_mfma_f32_16x16x32_bf16 v[6:9], v[186:189], v[178:181], v[6:9]
	v_mfma_f32_16x16x32_bf16 v[2:5], v[222:225], v[178:181], v[2:5]
	v_mfma_f32_16x16x32_bf16 v[34:37], v[186:189], v[118:121], v[86:89]
	v_mfma_f32_16x16x32_bf16 v[38:41], v[222:225], v[118:121], v[82:85]
	v_mfma_f32_16x16x32_bf16 v[42:45], v[186:189], v[134:137], v[70:73]
	v_mfma_f32_16x16x32_bf16 v[46:49], v[222:225], v[134:137], v[54:57]
	v_mfma_f32_16x16x32_bf16 v[22:25], v[208:211], v[174:177], v[22:25]
	v_mfma_f32_16x16x32_bf16 v[18:21], v[226:229], v[174:177], v[18:21]
	v_mfma_f32_16x16x32_bf16 v[6:9], v[208:211], v[182:185], v[6:9]
	v_mfma_f32_16x16x32_bf16 v[2:5], v[226:229], v[182:185], v[2:5]
	v_mfma_f32_16x16x32_bf16 v[34:37], v[208:211], v[130:133], v[34:37]
	v_mfma_f32_16x16x32_bf16 v[38:41], v[226:229], v[130:133], v[38:41]
	v_mfma_f32_16x16x32_bf16 v[42:45], v[208:211], v[146:149], v[42:45]
	v_mfma_f32_16x16x32_bf16 v[46:49], v[226:229], v[146:149], v[46:49]
	s_setprio 0
	s_add_i32 s67, 0, 0x18000
	v_add_u32_e32 v1, s67, v191
	s_barrier
	ds_read_b128 v[54:57], v1
	ds_read_b128 v[70:73], v1 offset:1024
	ds_read_b128 v[82:85], v1 offset:2048
	ds_read_b128 v[86:89], v1 offset:3072
	s_add_u32 s4, s48, 0x40000
	s_addc_u32 s5, s49, 0
	s_mov_b32 m0, s55
	v_lshl_add_u64 v[134:135], s[4:5], 0, v[164:165]
	ds_read_b128 v[118:121], v206 offset:32768
	ds_read_b128 v[130:133], v206 offset:33792
	ds_read_b128 v[170:173], v206 offset:34816
	ds_read_b128 v[174:177], v206 offset:35840
	ds_read_b128 v[178:181], v206 offset:36864
	ds_read_b128 v[182:185], v206 offset:37888
	ds_read_b128 v[186:189], v206 offset:38912
	ds_read_b128 v[208:211], v206 offset:39936
	global_load_lds_dwordx4 v[134:135], off
	v_lshl_add_u64 v[134:135], s[4:5], 0, v[162:163]
	s_mov_b32 m0, s56
	s_nop 0
	global_load_lds_dwordx4 v[134:135], off
	s_waitcnt lgkmcnt(8)
	s_barrier
	s_waitcnt lgkmcnt(0)
	s_setprio 1
	s_waitcnt lgkmcnt(0)
	v_mfma_f32_16x16x32_bf16 v[134:137], v[54:57], v[118:121], v[158:161]
	v_mfma_f32_16x16x32_bf16 v[158:161], v[70:73], v[130:133], v[134:137]
	v_mfma_f32_16x16x32_bf16 v[134:137], v[82:85], v[118:121], v[154:157]
	v_mfma_f32_16x16x32_bf16 v[154:157], v[86:89], v[130:133], v[134:137]
	v_mfma_f32_16x16x32_bf16 v[134:137], v[54:57], v[170:173], v[142:145]
	v_mfma_f32_16x16x32_bf16 v[142:145], v[70:73], v[174:177], v[134:137]
	v_mfma_f32_16x16x32_bf16 v[134:137], v[82:85], v[170:173], v[138:141]
	v_mfma_f32_16x16x32_bf16 v[126:129], v[54:57], v[178:181], v[126:129]
	v_mfma_f32_16x16x32_bf16 v[122:125], v[82:85], v[178:181], v[122:125]
	v_mfma_f32_16x16x32_bf16 v[110:113], v[54:57], v[186:189], v[110:113]
	v_mfma_f32_16x16x32_bf16 v[106:109], v[82:85], v[186:189], v[106:109]
	v_mfma_f32_16x16x32_bf16 v[138:141], v[86:89], v[174:177], v[134:137]
	v_mfma_f32_16x16x32_bf16 v[126:129], v[70:73], v[182:185], v[126:129]
	v_mfma_f32_16x16x32_bf16 v[122:125], v[86:89], v[182:185], v[122:125]
	v_mfma_f32_16x16x32_bf16 v[110:113], v[70:73], v[208:211], v[110:113]
	v_mfma_f32_16x16x32_bf16 v[106:109], v[86:89], v[208:211], v[106:109]
	s_setprio 0
	s_barrier
	s_add_i32 s48, 0, 0x1c000
	s_add_i32 s4, s67, s52
	v_add_u32_e32 v1, s48, v191
	v_lshl_add_u64 v[134:135], v[214:215], 0, s[22:23]
	s_mov_b32 m0, s4
	ds_read_b128 v[222:225], v1
	ds_read_b128 v[226:229], v1 offset:1024
	ds_read_b128 v[230:233], v1 offset:2048
	ds_read_b128 v[234:237], v1 offset:3072
	global_load_lds_dwordx4 v[134:135], off
	v_lshl_add_u64 v[134:135], v[238:239], 0, s[22:23]
	s_add_i32 m0, s4, 0x2000
	s_nop 0
	global_load_lds_dwordx4 v[134:135], off
	s_barrier
	s_waitcnt lgkmcnt(0)
	s_setprio 1
	s_waitcnt lgkmcnt(0)
	v_mfma_f32_16x16x32_bf16 v[50:53], v[230:233], v[118:121], v[50:53]
	v_mfma_f32_16x16x32_bf16 v[134:137], v[222:225], v[118:121], v[150:153]
	v_mfma_f32_16x16x32_bf16 v[146:149], v[234:237], v[130:133], v[50:53]
	v_mfma_f32_16x16x32_bf16 v[50:53], v[222:225], v[170:173], v[58:61]
	v_mfma_f32_16x16x32_bf16 v[150:153], v[226:229], v[130:133], v[134:137]
	v_mfma_f32_16x16x32_bf16 v[134:137], v[226:229], v[174:177], v[50:53]
	v_mfma_f32_16x16x32_bf16 v[50:53], v[230:233], v[170:173], v[62:65]
	v_mfma_f32_16x16x32_bf16 v[130:133], v[234:237], v[174:177], v[50:53]
	v_mfma_f32_16x16x32_bf16 v[50:53], v[222:225], v[178:181], v[66:69]
	v_mfma_f32_16x16x32_bf16 v[118:121], v[226:229], v[182:185], v[50:53]
	v_mfma_f32_16x16x32_bf16 v[50:53], v[230:233], v[178:181], v[114:117]
	v_mfma_f32_16x16x32_bf16 v[114:117], v[234:237], v[182:185], v[50:53]
	v_mfma_f32_16x16x32_bf16 v[50:53], v[222:225], v[186:189], v[102:105]
	v_mfma_f32_16x16x32_bf16 v[102:105], v[226:229], v[208:211], v[50:53]
	v_mfma_f32_16x16x32_bf16 v[50:53], v[230:233], v[186:189], v[98:101]
	v_mfma_f32_16x16x32_bf16 v[98:101], v[234:237], v[208:211], v[50:53]
	s_setprio 0
	s_mov_b32 m0, s58
	v_lshl_add_u64 v[186:187], v[240:241], 0, s[22:23]
	s_barrier
	s_nop 2
	ds_read_b128 v[50:53], v206 offset:49152
	ds_read_b128 v[58:61], v206 offset:50176
	ds_read_b128 v[62:65], v206 offset:51200
	ds_read_b128 v[66:69], v206 offset:52224
	ds_read_b128 v[170:173], v206 offset:53248
	ds_read_b128 v[174:177], v206 offset:54272
	ds_read_b128 v[178:181], v206 offset:55296
	ds_read_b128 v[182:185], v206 offset:56320
	global_load_lds_dwordx4 v[186:187], off
	v_lshl_add_u64 v[186:187], v[242:243], 0, s[22:23]
	s_mov_b32 m0, s59
	s_nop 0
	global_load_lds_dwordx4 v[186:187], off
	s_barrier
	s_waitcnt lgkmcnt(0)
	s_setprio 1
	s_waitcnt lgkmcnt(0)
	v_mfma_f32_16x16x32_bf16 v[94:97], v[54:57], v[50:53], v[94:97]
	v_mfma_f32_16x16x32_bf16 v[90:93], v[82:85], v[50:53], v[90:93]
	v_mfma_f32_16x16x32_bf16 v[78:81], v[54:57], v[62:65], v[78:81]
	v_mfma_f32_16x16x32_bf16 v[74:77], v[82:85], v[62:65], v[74:77]
	v_mfma_f32_16x16x32_bf16 v[30:33], v[54:57], v[170:173], v[30:33]
	v_mfma_f32_16x16x32_bf16 v[26:29], v[82:85], v[170:173], v[26:29]
	v_mfma_f32_16x16x32_bf16 v[14:17], v[54:57], v[178:181], v[14:17]
	v_mfma_f32_16x16x32_bf16 v[10:13], v[82:85], v[178:181], v[10:13]
	v_mfma_f32_16x16x32_bf16 v[94:97], v[70:73], v[58:61], v[94:97]
	v_mfma_f32_16x16x32_bf16 v[90:93], v[86:89], v[58:61], v[90:93]
	v_mfma_f32_16x16x32_bf16 v[78:81], v[70:73], v[66:69], v[78:81]
	v_mfma_f32_16x16x32_bf16 v[74:77], v[86:89], v[66:69], v[74:77]
	v_mfma_f32_16x16x32_bf16 v[30:33], v[70:73], v[174:177], v[30:33]
	v_mfma_f32_16x16x32_bf16 v[26:29], v[86:89], v[174:177], v[26:29]
	v_mfma_f32_16x16x32_bf16 v[14:17], v[70:73], v[182:185], v[14:17]
	v_mfma_f32_16x16x32_bf16 v[10:13], v[86:89], v[182:185], v[10:13]
	s_setprio 0
	s_barrier
	s_add_u32 s4, s46, 0x40080
	s_addc_u32 s5, s47, 0
	s_add_i32 s46, s48, s52
	v_lshl_add_u64 v[54:55], s[4:5], 0, v[164:165]
	s_mov_b32 m0, s46
	s_nop 0
	global_load_lds_dwordx4 v[54:55], off
	v_lshl_add_u64 v[54:55], s[4:5], 0, v[162:163]
	s_add_i32 m0, s46, 0x2000
	s_nop 0
	global_load_lds_dwordx4 v[54:55], off
	s_waitcnt vmcnt(6)
	s_barrier
	s_setprio 1
	v_mfma_f32_16x16x32_bf16 v[34:37], v[222:225], v[50:53], v[34:37]
	v_mfma_f32_16x16x32_bf16 v[86:89], v[226:229], v[58:61], v[34:37]
	v_mfma_f32_16x16x32_bf16 v[34:37], v[230:233], v[50:53], v[38:41]
	v_mfma_f32_16x16x32_bf16 v[82:85], v[234:237], v[58:61], v[34:37]
	v_mfma_f32_16x16x32_bf16 v[34:37], v[222:225], v[62:65], v[42:45]
	v_mfma_f32_16x16x32_bf16 v[70:73], v[226:229], v[66:69], v[34:37]
	v_mfma_f32_16x16x32_bf16 v[34:37], v[230:233], v[62:65], v[46:49]
	v_mfma_f32_16x16x32_bf16 v[22:25], v[222:225], v[170:173], v[22:25]
	v_mfma_f32_16x16x32_bf16 v[18:21], v[230:233], v[170:173], v[18:21]
	v_mfma_f32_16x16x32_bf16 v[6:9], v[222:225], v[178:181], v[6:9]
	v_mfma_f32_16x16x32_bf16 v[2:5], v[230:233], v[178:181], v[2:5]
	v_mfma_f32_16x16x32_bf16 v[54:57], v[234:237], v[66:69], v[34:37]
	v_mfma_f32_16x16x32_bf16 v[22:25], v[226:229], v[174:177], v[22:25]
	v_mfma_f32_16x16x32_bf16 v[18:21], v[234:237], v[174:177], v[18:21]
	v_mfma_f32_16x16x32_bf16 v[6:9], v[226:229], v[182:185], v[6:9]
	v_mfma_f32_16x16x32_bf16 v[2:5], v[234:237], v[182:185], v[2:5]
	s_setprio 0
	s_add_i32 s66, s66, 2
	s_add_u32 s64, s64, 0x100
	s_addc_u32 s65, s65, 0
	s_cmp_gt_u32 s66, 13
	s_mov_b64 s[4:5], s[36:37]
	s_barrier
	s_cbranch_scc0 .LBB0_212
	v_lshl_or_b32 v208, s3, 8, v192
	v_mov_b32_e32 v1, v190
	v_ashrrev_i32_e32 v209, 31, v208
	v_lshlrev_b64 v[34:35], 2, v[208:209]
	v_lshl_add_u64 v[36:37], s[8:9], 0, v[34:35]
	v_lshlrev_b32_e32 v250, 2, v192
	v_add_u32_e32 v250, 0x20840, v250
	ds_read_b128 v[62:65], v250
	ds_read_b128 v[50:53], v250 offset:16
	v_lshl_add_u64 v[34:35], s[10:11], 0, v[34:35]
	ds_read_b128 v[66:69], v250 offset:1024
	ds_read_b128 v[42:45], v250 offset:1040
	ds_read_b128 v[58:61], v250 offset:512
	ds_read_b128 v[38:41], v250 offset:528
	ds_read_b128 v[46:49], v250 offset:1536
	s_nop 0
	ds_read_b128 v[34:37], v250 offset:1552
	s_lshl_b32 s37, s27, 8
	v_lshl_add_u32 v170, v1, 3, 0
	v_add_u32_e32 v170, 0x20040, v170
	ds_read_b64 v[188:189], v170
	s_mov_b32 s4, 0xbf3a00e3
	s_cmp_gt_i32 s3, 3
	v_mov_b64_e32 v[176:177], s[4:5]
	s_cselect_b64 s[4:5], -1, 0
	s_and_b64 s[46:47], s[40:41], s[4:5]
	s_mov_b32 s4, 0x3f07dc22
	s_mov_b32 s38, 0x3f35f0e3
	s_mov_b32 s48, 0xbe11a98e
	s_mov_b32 s62, 0x3e027906
	s_lshl_b32 s3, s3, 2
	s_and_b32 s36, s3, 12
	s_mov_b32 s3, 0x1020000
	v_add_u32_e32 v170, s37, v1
	v_lshlrev_b32_e32 v1, 10, v170
	s_waitcnt lgkmcnt(0)
	v_xor_b32_e32 v65, 0x80000000, v65
	v_xor_b32_e32 v64, 0x80000000, v64
	v_pk_fma_f32 v[158:159], v[62:63], v[188:189], v[158:159] op_sel_hi:[1,0,1] neg_lo:[1,0,0] neg_hi:[1,0,0]
	v_xor_b32_e32 v53, 0x80000000, v53
	v_xor_b32_e32 v52, 0x80000000, v52
	v_pk_fma_f32 v[154:155], v[50:51], v[188:189], v[154:155] op_sel_hi:[1,0,1] neg_lo:[1,0,0] neg_hi:[1,0,0]
	v_pk_fma_f32 v[160:161], v[64:65], v[188:189], v[160:161] op_sel_hi:[1,0,1]
	v_pk_fma_f32 v[158:159], v[188:189], v[158:159], v[66:67] op_sel:[1,0,0]
	v_pk_fma_f32 v[172:173], v[52:53], v[188:189], v[156:157] op_sel_hi:[1,0,1]
	v_pk_fma_f32 v[156:157], v[188:189], v[154:155], v[42:43] op_sel:[1,0,0]
	v_pk_fma_f32 v[154:155], v[188:189], v[160:161], v[68:69] op_sel:[1,0,0]
	v_fma_f32 v175, |v159|, s1, 1.0
	v_fma_f32 v171, |v158|, s1, 1.0
	v_pk_fma_f32 v[160:161], v[188:189], v[172:173], v[44:45] op_sel:[1,0,0]
	v_fma_f32 v172, |v156|, s1, 1.0
	v_rcp_f32_e32 v175, v175
	v_fma_f32 v187, |v155|, s1, 1.0
	v_mul_f32_e32 v174, v158, v158
	v_rcp_f32_e32 v182, v171
	v_rcp_f32_e32 v183, v172
	v_rcp_f32_e32 v215, v187
	v_mul_f32_e32 v173, v156, v156
	v_fma_f32 v179, |v157|, s1, 1.0
	v_mul_f32_e32 v180, v157, v157
	v_mul_f32_e32 v171, 0xbf38aa3b, v174
	v_mul_f32_e32 v186, v154, v154
	v_fma_f32 v181, |v154|, s1, 1.0
	v_mul_f32_e32 v172, 0xbf38aa3b, v173
	v_rcp_f32_e32 v185, v179
	v_mul_f32_e32 v173, 0xbf38aa3b, v180
	v_fma_f32 v179, |v160|, s1, 1.0
	v_mul_f32_e32 v209, v160, v160
	v_exp_f32_e32 v180, v171
	v_mul_f32_e32 v171, 0xbf38aa3b, v186
	v_fma_f32 v211, |v161|, s1, 1.0
	v_rcp_f32_e32 v184, v181
	v_exp_f32_e32 v181, v172
	v_rcp_f32_e32 v210, v179
	v_mul_f32_e32 v179, 0xbf38aa3b, v209
	v_exp_f32_e32 v172, v171
	v_fmamk_f32 v171, v175, 0x3f07dc22, v218
	v_rcp_f32_e32 v211, v211
	v_exp_f32_e32 v214, v179
	v_pk_fma_f32 v[186:187], v[182:183], s[4:5], v[176:177] op_sel_hi:[1,0,0]
	v_fmaak_f32 v171, v175, v171, 0x3f35f0e3
	v_fmamk_f32 v179, v215, 0x3f07dc22, v218
	v_pk_fma_f32 v[186:187], v[182:183], v[186:187], s[38:39] op_sel_hi:[1,1,0]
	v_fmaak_f32 v171, v175, v171, 0xbe11a98e
	v_fmaak_f32 v179, v215, v179, 0x3f35f0e3
	v_pk_fma_f32 v[186:187], v[182:183], v[186:187], s[48:49] op_sel_hi:[1,1,0]
	v_fmaak_f32 v171, v175, v171, 0x3e027906
	v_fmaak_f32 v179, v215, v179, 0xbe11a98e
	v_mul_f32_e32 v212, v161, v161
	v_pk_fma_f32 v[224:225], v[182:183], v[186:187], s[62:63] op_sel_hi:[1,1,0]
	v_mul_f32_e32 v186, v175, v171
	v_fmaak_f32 v171, v215, v179, 0x3e027906
	v_pk_fma_f32 v[222:223], v[184:185], s[4:5], v[176:177] op_sel_hi:[1,0,0]
	v_pk_mul_f32 v[224:225], v[182:183], v[224:225]
	v_mul_f32_e32 v182, v215, v171
	v_mul_f32_e32 v171, 0xbf38aa3b, v212
	v_pk_fma_f32 v[176:177], v[210:211], s[4:5], v[176:177] op_sel_hi:[1,0,0]
	v_exp_f32_e32 v215, v171
	v_pk_fma_f32 v[176:177], v[210:211], v[176:177], s[38:39] op_sel_hi:[1,1,0]
	v_cmp_gt_f32_e32 vcc, 0, v161
	v_pk_fma_f32 v[176:177], v[210:211], v[176:177], s[48:49] op_sel_hi:[1,1,0]
	v_pk_fma_f32 v[150:151], v[58:59], v[188:189], v[150:151] op_sel_hi:[1,0,1] neg_lo:[1,0,0] neg_hi:[1,0,0]
	v_pk_fma_f32 v[176:177], v[210:211], v[176:177], s[62:63] op_sel_hi:[1,1,0]
	v_pk_fma_f32 v[150:151], v[188:189], v[150:151], v[46:47] op_sel:[1,0,0]
	v_pk_mul_f32 v[176:177], v[210:211], v[176:177]
	v_fma_f32 v175, |v150|, s1, 1.0
	v_pk_mul_f32 v[176:177], v[214:215], v[176:177]
	v_rcp_f32_e32 v175, v175
	v_pk_mul_f32 v[210:211], v[160:161], v[176:177]
	v_pk_fma_f32 v[176:177], v[160:161], v[176:177], v[160:161] neg_lo:[1,0,0] neg_hi:[1,0,0]
	v_mul_f32_e32 v178, v159, v159
	v_cndmask_b32_e32 v177, v177, v211, vcc
	v_cmp_gt_f32_e32 vcc, 0, v160
	v_xor_b32_e32 v61, 0x80000000, v61
	v_xor_b32_e32 v60, 0x80000000, v60
	v_cndmask_b32_e32 v176, v176, v210, vcc
	v_mul_f32_e32 v160, v176, v176
	v_pk_fma_f32 v[160:161], v[176:177], v[176:177], v[160:161] op_sel_hi:[1,1,0]
	v_mul_f32_e32 v174, 0xbf38aa3b, v178
	v_lshrrev_b32_e32 v160, 10, v208
	v_mul_f32_e32 v207, v155, v155
	v_mul_lo_u32 v160, v160, s3
	s_movk_i32 s4, 0x3ff
	v_pk_fma_f32 v[152:153], v[60:61], v[188:189], v[152:153] op_sel_hi:[1,0,1]
	v_exp_f32_e32 v178, v174
	v_mul_f32_e32 v174, 0xbf38aa3b, v207
	v_and_or_b32 v207, v208, s4, v160
	v_add_u32_e32 v171, 0x80, v208
	v_pk_fma_f32 v[208:209], v[188:189], v[152:153], v[48:49] op_sel:[1,0,0]
	v_fmamk_f32 v152, v175, 0x3f07dc22, v218
	v_fmaak_f32 v152, v175, v152, 0x3f35f0e3
	v_mul_f32_e32 v153, v150, v150
	v_mul_f32_e32 v153, 0xbf38aa3b, v153
	v_fmaak_f32 v152, v175, v152, 0xbe11a98e
	v_exp_f32_e32 v153, v153
	v_fmaak_f32 v152, v175, v152, 0x3e027906
	v_mul_f32_e32 v152, v175, v152
	v_fma_f32 v175, |v151|, s1, 1.0
	v_rcp_f32_e32 v175, v175
	v_mul_f32_e32 v152, v153, v152
	v_mul_f32_e32 v153, v150, v152
	v_fma_f32 v152, -v150, v152, v150
	v_cmp_gt_f32_e32 vcc, 0, v150
	v_pk_fma_f32 v[146:147], v[38:39], v[188:189], v[146:147] op_sel_hi:[1,0,1] neg_lo:[1,0,0] neg_hi:[1,0,0]
	v_xor_b32_e32 v41, 0x80000000, v41
	v_cndmask_b32_e32 v150, v152, v153, vcc
	v_fmamk_f32 v152, v175, 0x3f07dc22, v218
	v_fmaak_f32 v152, v175, v152, 0x3f35f0e3
	v_mul_f32_e32 v153, v151, v151
	v_fmaak_f32 v152, v175, v152, 0xbe11a98e
	v_mul_f32_e32 v153, 0xbf38aa3b, v153
	v_fmaak_f32 v152, v175, v152, 0x3e027906
	v_exp_f32_e32 v153, v153
	v_mul_f32_e32 v152, v175, v152
	v_fma_f32 v175, |v208|, s1, 1.0
	v_rcp_f32_e32 v175, v175
	v_mul_f32_e32 v152, v153, v152
	v_mul_f32_e32 v153, v151, v152
	v_fma_f32 v152, -v151, v152, v151
	v_cmp_gt_f32_e32 vcc, 0, v151
	v_fmamk_f32 v151, v175, 0x3f07dc22, v218
	v_fmaak_f32 v151, v175, v151, 0x3f35f0e3
	v_cndmask_b32_e32 v152, v152, v153, vcc
	v_mul_f32_e32 v153, v208, v208
	v_mul_f32_e32 v153, 0xbf38aa3b, v153
	v_fmaak_f32 v151, v175, v151, 0xbe11a98e
	v_exp_f32_e32 v153, v153
	v_fmaak_f32 v151, v175, v151, 0x3e027906
	v_mul_f32_e32 v151, v175, v151
	v_fma_f32 v175, |v209|, s1, 1.0
	v_rcp_f32_e32 v175, v175
	v_mul_f32_e32 v151, v153, v151
	v_mul_f32_e32 v153, v208, v151
	v_fma_f32 v151, -v208, v151, v208
	v_cmp_gt_f32_e32 vcc, 0, v208
	v_pk_fma_f32 v[146:147], v[188:189], v[146:147], v[34:35] op_sel:[1,0,0]
	v_xor_b32_e32 v40, 0x80000000, v40
	v_cndmask_b32_e32 v208, v151, v153, vcc
	v_fmamk_f32 v151, v175, 0x3f07dc22, v218
	v_fmaak_f32 v151, v175, v151, 0x3f35f0e3
	v_fmaak_f32 v151, v175, v151, 0xbe11a98e
	v_fmaak_f32 v151, v175, v151, 0x3e027906
	v_mul_f32_e32 v151, v175, v151
	v_fma_f32 v175, |v146|, s1, 1.0
	v_rcp_f32_e32 v175, v175
	v_mul_f32_e32 v183, v146, v146
	v_mul_f32_e32 v153, v209, v209
	v_mul_f32_e32 v183, 0xbf38aa3b, v183
	v_fmamk_f32 v179, v175, 0x3f07dc22, v218
	v_mul_f32_e32 v153, 0xbf38aa3b, v153
	v_fmaak_f32 v179, v175, v179, 0x3f35f0e3
	v_exp_f32_e32 v183, v183
	v_exp_f32_e32 v153, v153
	v_fmaak_f32 v179, v175, v179, 0xbe11a98e
	v_fmaak_f32 v179, v175, v179, 0x3e027906
	v_mul_f32_e32 v175, v175, v179
	v_mul_f32_e32 v175, v183, v175
	v_fma_f32 v183, |v147|, s1, 1.0
	v_mul_f32_e32 v151, v153, v151
	v_rcp_f32_e32 v183, v183
	v_mul_f32_e32 v153, v209, v151
	v_fma_f32 v151, -v209, v151, v209
	v_cmp_gt_f32_e32 vcc, 0, v209
	v_mul_f32_e32 v179, v146, v175
	v_fma_f32 v175, -v146, v175, v146
	v_cndmask_b32_e32 v210, v151, v153, vcc
	v_cmp_gt_f32_e32 vcc, 0, v146
	v_pk_fma_f32 v[148:149], v[40:41], v[188:189], v[148:149] op_sel_hi:[1,0,1]
	v_fmamk_f32 v146, v183, 0x3f07dc22, v218
	v_cndmask_b32_e32 v214, v175, v179, vcc
	v_mul_f32_e32 v175, v147, v147
	v_mul_f32_e32 v175, 0xbf38aa3b, v175
	v_pk_fma_f32 v[148:149], v[188:189], v[148:149], v[36:37] op_sel:[1,0,0]
	v_fmaak_f32 v146, v183, v146, 0x3f35f0e3
	v_exp_f32_e32 v175, v175
	v_fmaak_f32 v146, v183, v146, 0xbe11a98e
	v_fma_f32 v179, |v148|, s1, 1.0
	v_fmaak_f32 v146, v183, v146, 0x3e027906
	v_rcp_f32_e32 v179, v179
	v_pk_fma_f32 v[222:223], v[184:185], v[222:223], s[38:39] op_sel_hi:[1,1,0]
	v_mul_f32_e32 v146, v183, v146
	v_pk_fma_f32 v[222:223], v[184:185], v[222:223], s[48:49] op_sel_hi:[1,1,0]
	v_mul_f32_e32 v146, v175, v146
	v_pk_fma_f32 v[222:223], v[184:185], v[222:223], s[62:63] op_sel_hi:[1,1,0]
	v_mul_f32_e32 v175, v147, v146
	v_fma_f32 v146, -v147, v146, v147
	v_cmp_gt_f32_e32 vcc, 0, v147
	v_mul_f32_e32 v147, v148, v148
	v_pk_mul_f32 v[184:185], v[184:185], v[222:223]
	v_cndmask_b32_e32 v222, v146, v175, vcc
	v_fmamk_f32 v146, v179, 0x3f07dc22, v218
	v_mul_f32_e32 v147, 0xbf38aa3b, v147
	v_fmaak_f32 v146, v179, v146, 0x3f35f0e3
	v_exp_f32_e32 v147, v147
	v_fmaak_f32 v146, v179, v146, 0xbe11a98e
	v_fmaak_f32 v146, v179, v146, 0x3e027906
	v_fma_f32 v175, |v149|, s1, 1.0
	v_mul_f32_e32 v146, v179, v146
	v_rcp_f32_e32 v175, v175
	v_mul_f32_e32 v146, v147, v146
	v_mul_f32_e32 v147, v148, v146
	v_fma_f32 v146, -v148, v146, v148
	v_cmp_gt_f32_e32 vcc, 0, v148
	v_exp_f32_e32 v173, v173
	v_exp_f32_e32 v174, v174
	v_cndmask_b32_e32 v226, v146, v147, vcc
	v_mul_f32_e32 v147, v149, v149
	v_fmamk_f32 v146, v175, 0x3f07dc22, v218
	v_mul_f32_e32 v147, 0xbf38aa3b, v147
	v_fmaak_f32 v146, v175, v146, 0x3f35f0e3
	v_exp_f32_e32 v147, v147
	v_fmaak_f32 v146, v175, v146, 0xbe11a98e
	v_fmaak_f32 v146, v175, v146, 0x3e027906
	v_mul_f32_e32 v146, v175, v146
	v_mul_f32_e32 v146, v147, v146
	v_mul_f32_e32 v147, v149, v146
	v_fma_f32 v146, -v149, v146, v149
	v_cmp_gt_f32_e32 vcc, 0, v149
	v_mov_b32_e32 v179, v181
	v_mov_b32_e32 v187, v225
	v_cndmask_b32_e32 v228, v146, v147, vcc
	v_lshrrev_b32_e32 v146, 10, v171
	v_mul_lo_u32 v146, v146, s3
	v_and_or_b32 v188, v171, s4, v146
	v_pk_mul_f32 v[146:147], v[180:181], v[224:225]
	v_pk_mul_f32 v[148:149], v[178:179], v[186:187]
	v_mov_b32_e32 v178, v158
	v_mov_b32_e32 v179, v156
	v_pk_mov_b32 v[186:187], v[158:159], v[156:157] op_sel:[1,0]
	v_pk_mul_f32 v[180:181], v[178:179], v[146:147]
	v_pk_mul_f32 v[224:225], v[186:187], v[148:149]
	v_pk_fma_f32 v[146:147], v[178:179], v[146:147], v[178:179] neg_lo:[1,0,0] neg_hi:[1,0,0]
	v_pk_fma_f32 v[148:149], v[186:187], v[148:149], v[186:187] neg_lo:[1,0,0] neg_hi:[1,0,0]
	v_cmp_gt_f32_e32 vcc, 0, v156
	v_cmp_gt_f32_e64 s[4:5], 0, v158
	v_mov_b32_e32 v175, v173
	v_cndmask_b32_e32 v179, v147, v181, vcc
	v_cndmask_b32_e32 v181, v149, v225, vcc
	v_cmp_gt_f32_e32 vcc, 0, v159
	v_mov_b32_e32 v183, v185
	v_cndmask_b32_e64 v178, v146, v180, s[4:5]
	v_cndmask_b32_e32 v180, v148, v224, vcc
	v_pk_mul_f32 v[148:149], v[172:173], v[184:185]
	v_pk_mul_f32 v[158:159], v[174:175], v[182:183]
	v_mov_b32_e32 v156, v154
	v_mov_b32_e32 v174, v155
	v_mov_b32_e32 v175, v157
	v_pk_mul_f32 v[172:173], v[156:157], v[148:149]
	v_pk_mul_f32 v[182:183], v[174:175], v[158:159]
	v_pk_fma_f32 v[148:149], v[156:157], v[148:149], v[156:157] neg_lo:[1,0,0] neg_hi:[1,0,0]
	v_pk_fma_f32 v[158:159], v[174:175], v[158:159], v[174:175] neg_lo:[1,0,0] neg_hi:[1,0,0]
	v_cmp_gt_f32_e32 vcc, 0, v157
	v_cmp_gt_f32_e64 s[4:5], 0, v154
	v_add_lshl_u32 v160, v1, v207, 1
	v_cndmask_b32_e32 v157, v149, v173, vcc
	v_cndmask_b32_e64 v156, v148, v172, s[4:5]
	v_cndmask_b32_e32 v159, v159, v183, vcc
	v_cmp_gt_f32_e32 vcc, 0, v155
	v_pk_mul_f32 v[174:175], v[156:157], v[156:157]
	v_mul_f32_e32 v151, v150, v150
	v_cndmask_b32_e32 v158, v158, v182, vcc
	v_mul_f32_e32 v153, v152, v152
	v_mul_f32_e32 v209, v208, v208
	v_mul_f32_e32 v211, v210, v210
	v_mul_f32_e32 v215, v214, v214
	v_mul_f32_e32 v223, v222, v222
	v_mul_f32_e32 v227, v226, v226
	v_mul_f32_e32 v229, v228, v228
	v_add_lshl_u32 v171, v1, v188, 1
	v_cvt_pk_bf16_f32 v146, v178, v180
	v_cvt_pk_bf16_f32 v147, v156, v158
	v_pk_mul_f32 v[154:155], v[178:179], v[178:179]
	v_pk_mul_f32 v[172:173], v[180:181], v[180:181]
	v_pk_mul_f32 v[182:183], v[158:159], v[158:159]
	v_pk_mov_b32 v[154:155], v[178:179], v[154:155] op_sel:[1,0]
	v_pk_mov_b32 v[172:173], v[156:157], v[172:173] op_sel:[1,0]
	v_cvt_pk_bf16_f32 v148, v179, v157
	v_mov_b32_e32 v1, v161
	v_pk_add_f32 v[154:155], v[154:155], v[172:173]
	v_mov_b32_e32 v172, v176
	v_mov_b32_e32 v173, v174
	v_pk_mov_b32 v[174:175], v[176:177], v[182:183] op_sel:[1,0]
	v_cvt_pk_bf16_f32 v149, v176, v177
	buffer_store_dwordx4 v[146:149], v160, s[28:31], 0 offen sc1
	v_pk_add_f32 v[172:173], v[172:173], v[174:175]
	v_pk_mul_f32 v[174:175], v[178:179], v[180:181]
	v_pk_add_f32 v[154:155], v[154:155], v[172:173]
	v_pk_add_f32 v[172:173], v[178:179], v[180:181]
	s_nop 0
	v_mov_b32_e32 v173, v175
	v_pk_add_f32 v[174:175], v[156:157], v[158:159]
	v_pk_mul_f32 v[156:157], v[156:157], v[158:159]
	s_nop 0
	v_mov_b32_e32 v175, v157
	v_pk_add_f32 v[156:157], v[172:173], v[174:175]
	s_nop 0
	v_pk_add_f32 v[156:157], v[156:157], v[0:1]
	s_nop 0
	v_pk_add_f32 v[154:155], v[154:155], v[156:157]
	v_cvt_pk_bf16_f32 v146, v150, v152
	v_pk_add_f32 v[148:149], v[150:151], v[152:153]
	v_pk_add_f32 v[150:151], v[208:209], v[210:211]
	v_cvt_pk_bf16_f32 v147, v208, v210
	s_nop 0
	v_pk_add_f32 v[148:149], v[148:149], v[150:151]
	s_nop 0
	v_pk_add_f32 v[150:151], v[148:149], v[154:155]
	v_pk_add_f32 v[152:153], v[214:215], v[222:223]
	v_pk_add_f32 v[154:155], v[226:227], v[228:229]
	v_cvt_pk_bf16_f32 v148, v214, v222
	v_cvt_pk_bf16_f32 v149, v226, v228
	buffer_store_dwordx4 v[146:149], v171, s[28:31], 0 offen sc1
	v_pk_add_f32 v[152:153], v[152:153], v[154:155]
	s_nop 0
	v_pk_add_f32 v[150:151], v[152:153], v[150:151]
	v_and_b32_e32 v146, 64, v216
	v_xor_b32_e32 v1, 16, v216
	v_add_u32_e32 v148, 64, v146
	v_cmp_lt_i32_e32 vcc, v1, v148
	s_nop 1
	v_cndmask_b32_e32 v1, v216, v1, vcc
	v_lshlrev_b32_e32 v174, 2, v1
	ds_bpermute_b32 v146, v174, v150
	ds_bpermute_b32 v147, v174, v151
	v_xor_b32_e32 v1, 32, v216
	v_cmp_lt_i32_e32 vcc, v1, v148
	s_waitcnt lgkmcnt(0)
	v_pk_add_f32 v[146:147], v[150:151], v[146:147]
	v_cndmask_b32_e32 v1, v216, v1, vcc
	v_lshlrev_b32_e32 v175, 2, v1
	ds_bpermute_b32 v148, v175, v146
	ds_bpermute_b32 v149, v175, v147
	s_and_saveexec_b64 s[4:5], s[46:47]
	s_cbranch_execz .LBB0_215
	v_ashrrev_i32_e32 v171, 31, v170
	v_lshlrev_b64 v[150:151], 7, v[170:171]
	v_lshl_add_u64 v[150:151], s[12:13], 0, v[150:151]
	s_lshl_b32 s38, s36, 3
	v_lshl_add_u64 v[150:151], v[150:151], 0, s[38:39]
	s_lshl_b32 s38, s57, 3
	v_lshl_add_u64 v[150:151], v[150:151], 0, s[38:39]
	s_waitcnt lgkmcnt(0)
	v_pk_add_f32 v[146:147], v[146:147], v[148:149]
	flat_store_dwordx2 v[150:151], v[146:147]

.LBB0_395:
	s_add_i32 s66, s66, 1
	s_mov_b64 s[36:37], s[20:21]
	s_mul_i32 s20, s66, s26
	s_add_i32 s42, s20, s2
	s_cmpk_gt_i32 s42, 0x3ff
	s_cselect_b64 s[52:53], -1, 0
	s_lshl_b32 s20, s42, 3
	s_and_b32 s20, s20, 56
	s_bfe_u32 s21, s42, 0x30003
	s_mov_b32 s3, s67
	s_or_b32 s67, s20, s21
	s_mov_b32 s27, s50
	s_ashr_i32 s50, s42, 6
	s_lshl_b32 s20, s67, 19
	s_mov_b64 s[4:5], s[48:49]
	s_add_u32 s48, s18, s20
	s_addc_u32 s49, s19, 0
	s_ashr_i32 s51, s50, 31
	s_lshl_b64 s[20:21], s[50:51], 19
	s_add_u32 s20, s16, s20
	s_addc_u32 s21, s17, s21
	s_cmpk_lt_i32 s42, 0x400
	s_cselect_b32 s46, s49, s5
	s_cselect_b32 s47, s48, s4
	s_cselect_b32 s51, s21, s37
	s_cselect_b32 s54, s20, s36
	s_add_u32 s55, s36, 0x100
	s_addc_u32 s56, s37, 0
	s_mov_b32 s57, -2
	s_add_u32 s36, s4, 0x100
	s_addc_u32 s37, s5, 0
	s_add_i32 s68, 0, 0x10000
	v_add_u32_e32 v30, s68, v204
	ds_read_b128 v[14:17], v30
	ds_read_b128 v[22:25], v30 offset:1024
	ds_read_b128 v[26:29], v30 offset:2048
	ds_read_b128 v[30:33], v30 offset:3072
	s_cmp_eq_u32 s57, 12
	s_cselect_b32 s45, s46, s37
	s_cselect_b32 s44, s47, s36
	s_cselect_b32 s43, s51, s56
	s_cselect_b32 s42, s54, s55
	v_lshl_add_u64 v[178:179], s[4:5], 0, v[188:189]
	s_add_i32 m0, s60, 0xc000
	ds_read_b128 v[38:41], v209
	ds_read_b128 v[42:45], v209 offset:1024
	ds_read_b128 v[46:49], v209 offset:2048
	ds_read_b128 v[54:57], v209 offset:3072
	ds_read_b128 v[58:61], v209 offset:4096
	ds_read_b128 v[62:65], v209 offset:5120
	ds_read_b128 v[66:69], v209 offset:6144
	ds_read_b128 v[70:73], v209 offset:7168
	global_load_lds_dwordx4 v[178:179], off
	v_lshl_add_u64 v[178:179], s[4:5], 0, v[186:187]
	s_add_i32 m0, s60, 0xe000
	s_nop 0
	global_load_lds_dwordx4 v[178:179], off
	s_waitcnt lgkmcnt(8)
	s_barrier
	s_waitcnt lgkmcnt(0)
	s_setprio 1
	s_waitcnt lgkmcnt(0)
	v_mfma_f32_16x16x32_bf16 v[174:177], v[14:17], v[38:41], 0
	v_mfma_f32_16x16x32_bf16 v[170:173], v[26:29], v[38:41], 0
	v_mfma_f32_16x16x32_bf16 v[158:161], v[14:17], v[46:49], 0
	v_mfma_f32_16x16x32_bf16 v[154:157], v[26:29], v[46:49], 0
	v_mfma_f32_16x16x32_bf16 v[142:145], v[14:17], v[58:61], 0
	v_mfma_f32_16x16x32_bf16 v[138:141], v[26:29], v[58:61], 0
	v_mfma_f32_16x16x32_bf16 v[126:129], v[14:17], v[66:69], 0
	v_mfma_f32_16x16x32_bf16 v[122:125], v[26:29], v[66:69], 0
	v_mfma_f32_16x16x32_bf16 v[174:177], v[22:25], v[42:45], v[174:177]
	v_mfma_f32_16x16x32_bf16 v[170:173], v[30:33], v[42:45], v[170:173]
	v_mfma_f32_16x16x32_bf16 v[158:161], v[22:25], v[54:57], v[158:161]
	v_mfma_f32_16x16x32_bf16 v[154:157], v[30:33], v[54:57], v[154:157]
	v_mfma_f32_16x16x32_bf16 v[142:145], v[22:25], v[62:65], v[142:145]
	v_mfma_f32_16x16x32_bf16 v[138:141], v[30:33], v[62:65], v[138:141]
	v_mfma_f32_16x16x32_bf16 v[126:129], v[22:25], v[70:73], v[126:129]
	v_mfma_f32_16x16x32_bf16 v[122:125], v[30:33], v[70:73], v[122:125]
	s_setprio 0
	s_barrier
	v_mbcnt_lo_u32_b32 v250, -1, 0
	v_mbcnt_hi_u32_b32 v250, -1, v250
	v_lshlrev_b32_e32 v250, 4, v250
	s_lshl_b32 s32, s27, 10
	s_add_u32 s90, s10, s32
	s_addc_u32 s91, s11, 0
	s_add_u32 s92, s12, s32
	s_addc_u32 s93, s13, 0
	s_and_b32 s32, s27, 3
	s_lshl_b32 s32, s32, 10
	s_add_u32 s98, s14, s32
	s_addc_u32 s99, s15, 0
	s_mov_b32 m0, 0x20840
	s_nop 0
	global_load_lds_dwordx4 v250, s[90:91]
	s_mov_b32 m0, 0x20c40
	s_nop 0
	global_load_lds_dwordx4 v250, s[92:93]
	s_mov_b32 m0, 0x21040
	s_nop 0
	global_load_lds_dwordx4 v250, s[98:99]
	s_add_i32 s69, 0, 0x14000
	v_add_u32_e32 v210, s69, v204
	s_add_i32 s4, s68, s59
	ds_read_b128 v[178:181], v210
	ds_read_b128 v[190:193], v210 offset:1024
	ds_read_b128 v[200:203], v210 offset:2048
	ds_read_b128 v[222:225], v210 offset:3072
	v_lshl_add_u64 v[210:211], s[42:43], 0, v[184:185]
	s_mov_b32 m0, s4
	v_lshl_add_u64 v[214:215], s[42:43], 0, v[182:183]
	global_load_lds_dwordx4 v[210:211], off
	s_add_i32 m0, s4, 0x2000
	s_nop 0
	global_load_lds_dwordx4 v[214:215], off
	s_barrier
	s_waitcnt lgkmcnt(0)
	s_setprio 1
	s_waitcnt lgkmcnt(0)
	v_mfma_f32_16x16x32_bf16 v[166:169], v[178:181], v[38:41], 0
	v_mfma_f32_16x16x32_bf16 v[38:41], v[200:203], v[38:41], 0
	v_mfma_f32_16x16x32_bf16 v[166:169], v[190:193], v[42:45], v[166:169]
	v_mfma_f32_16x16x32_bf16 v[38:41], v[222:225], v[42:45], v[38:41]
	v_mfma_f32_16x16x32_bf16 v[42:45], v[178:181], v[46:49], 0
	v_mfma_f32_16x16x32_bf16 v[46:49], v[200:203], v[46:49], 0
	v_mfma_f32_16x16x32_bf16 v[42:45], v[190:193], v[54:57], v[42:45]
	v_mfma_f32_16x16x32_bf16 v[46:49], v[222:225], v[54:57], v[46:49]
	v_mfma_f32_16x16x32_bf16 v[54:57], v[178:181], v[58:61], 0
	v_mfma_f32_16x16x32_bf16 v[58:61], v[200:203], v[58:61], 0
	v_mfma_f32_16x16x32_bf16 v[54:57], v[190:193], v[62:65], v[54:57]
	v_mfma_f32_16x16x32_bf16 v[58:61], v[222:225], v[62:65], v[58:61]
	v_mfma_f32_16x16x32_bf16 v[62:65], v[178:181], v[66:69], 0
	v_mfma_f32_16x16x32_bf16 v[66:69], v[200:203], v[66:69], 0
	v_mfma_f32_16x16x32_bf16 v[62:65], v[190:193], v[70:73], v[62:65]
	v_mfma_f32_16x16x32_bf16 v[66:69], v[222:225], v[70:73], v[66:69]
	s_setprio 0
	s_mov_b32 m0, s60
	v_lshl_add_u64 v[242:243], s[44:45], 0, v[184:185]
	s_barrier
	ds_read_b128 v[70:73], v209 offset:16384
	ds_read_b128 v[114:117], v209 offset:17408
	ds_read_b128 v[118:121], v209 offset:18432
	ds_read_b128 v[130:133], v209 offset:19456
	ds_read_b128 v[134:137], v209 offset:20480
	ds_read_b128 v[146:149], v209 offset:21504
	ds_read_b128 v[150:153], v209 offset:22528
	ds_read_b128 v[162:165], v209 offset:23552
	global_load_lds_dwordx4 v[242:243], off
	v_lshl_add_u64 v[244:245], s[44:45], 0, v[182:183]
	s_mov_b32 m0, s61
	s_nop 0
	global_load_lds_dwordx4 v[244:245], off
	s_barrier
	s_waitcnt lgkmcnt(0)
	s_setprio 1
	s_waitcnt lgkmcnt(0)
	v_mfma_f32_16x16x32_bf16 v[110:113], v[14:17], v[70:73], 0
	v_mfma_f32_16x16x32_bf16 v[106:109], v[26:29], v[70:73], 0
	v_mfma_f32_16x16x32_bf16 v[94:97], v[14:17], v[118:121], 0
	v_mfma_f32_16x16x32_bf16 v[90:93], v[26:29], v[118:121], 0
	v_mfma_f32_16x16x32_bf16 v[78:81], v[14:17], v[134:137], 0
	v_mfma_f32_16x16x32_bf16 v[74:77], v[26:29], v[134:137], 0
	v_mfma_f32_16x16x32_bf16 v[10:13], v[26:29], v[150:153], 0
	v_mfma_f32_16x16x32_bf16 v[110:113], v[22:25], v[114:117], v[110:113]
	v_mfma_f32_16x16x32_bf16 v[106:109], v[30:33], v[114:117], v[106:109]
	v_mfma_f32_16x16x32_bf16 v[94:97], v[22:25], v[130:133], v[94:97]
	v_mfma_f32_16x16x32_bf16 v[90:93], v[30:33], v[130:133], v[90:93]
	v_mfma_f32_16x16x32_bf16 v[78:81], v[22:25], v[146:149], v[78:81]
	v_mfma_f32_16x16x32_bf16 v[74:77], v[30:33], v[146:149], v[74:77]
	v_mfma_f32_16x16x32_bf16 v[14:17], v[14:17], v[150:153], 0
	v_mfma_f32_16x16x32_bf16 v[10:13], v[30:33], v[162:165], v[10:13]
	v_mfma_f32_16x16x32_bf16 v[14:17], v[22:25], v[162:165], v[14:17]
	s_setprio 0
	s_barrier
	s_add_u32 s4, s42, 0x40000
	s_addc_u32 s5, s43, 0
	s_add_i32 s68, s69, s59
	v_lshl_add_u64 v[18:19], s[4:5], 0, v[184:185]
	s_mov_b32 m0, s68
	s_nop 0
	global_load_lds_dwordx4 v[18:19], off
	v_lshl_add_u64 v[18:19], s[4:5], 0, v[182:183]
	s_add_i32 m0, s68, 0x2000
	s_nop 0
	global_load_lds_dwordx4 v[18:19], off
	s_waitcnt vmcnt(6)
	s_barrier
	s_setprio 1
	v_mfma_f32_16x16x32_bf16 v[18:21], v[178:181], v[70:73], 0
	v_mfma_f32_16x16x32_bf16 v[22:25], v[190:193], v[114:117], v[18:21]
	v_mfma_f32_16x16x32_bf16 v[18:21], v[200:203], v[70:73], 0
	v_mfma_f32_16x16x32_bf16 v[26:29], v[222:225], v[114:117], v[18:21]
	v_mfma_f32_16x16x32_bf16 v[18:21], v[178:181], v[118:121], 0
	v_mfma_f32_16x16x32_bf16 v[30:33], v[190:193], v[130:133], v[18:21]
	v_mfma_f32_16x16x32_bf16 v[18:21], v[200:203], v[118:121], 0
	v_mfma_f32_16x16x32_bf16 v[70:73], v[222:225], v[130:133], v[18:21]
	v_mfma_f32_16x16x32_bf16 v[18:21], v[178:181], v[134:137], 0
	v_mfma_f32_16x16x32_bf16 v[50:53], v[190:193], v[146:149], v[18:21]
	v_mfma_f32_16x16x32_bf16 v[18:21], v[200:203], v[134:137], 0
	v_mfma_f32_16x16x32_bf16 v[6:9], v[178:181], v[150:153], 0
	v_mfma_f32_16x16x32_bf16 v[2:5], v[200:203], v[150:153], 0
	v_mfma_f32_16x16x32_bf16 v[34:37], v[222:225], v[146:149], v[18:21]
	v_mfma_f32_16x16x32_bf16 v[6:9], v[190:193], v[162:165], v[6:9]
	v_mfma_f32_16x16x32_bf16 v[2:5], v[222:225], v[162:165], v[2:5]
	s_setprio 0
	s_add_i32 s68, 0, 0x18000
	v_add_u32_e32 v98, s68, v204
	s_barrier
	ds_read_b128 v[18:21], v98
	ds_read_b128 v[82:85], v98 offset:1024
	ds_read_b128 v[86:89], v98 offset:2048
	ds_read_b128 v[98:101], v98 offset:3072
	s_add_u32 s4, s44, 0x40000
	s_addc_u32 s5, s45, 0
	s_mov_b32 m0, s62
	v_lshl_add_u64 v[134:135], s[4:5], 0, v[184:185]
	ds_read_b128 v[102:105], v209 offset:32768
	ds_read_b128 v[114:117], v209 offset:33792
	ds_read_b128 v[118:121], v209 offset:34816
	ds_read_b128 v[130:133], v209 offset:35840
	ds_read_b128 v[178:181], v209 offset:36864
	ds_read_b128 v[190:193], v209 offset:37888
	ds_read_b128 v[200:203], v209 offset:38912
	ds_read_b128 v[222:225], v209 offset:39936
	global_load_lds_dwordx4 v[134:135], off
	v_lshl_add_u64 v[134:135], s[4:5], 0, v[182:183]
	s_mov_b32 m0, s63
	s_nop 0
	global_load_lds_dwordx4 v[134:135], off
	s_waitcnt lgkmcnt(8)
	s_barrier
	s_waitcnt lgkmcnt(0)
	s_setprio 1
	s_waitcnt lgkmcnt(0)
	v_mfma_f32_16x16x32_bf16 v[134:137], v[18:21], v[102:105], v[174:177]
	v_mfma_f32_16x16x32_bf16 v[174:177], v[82:85], v[114:117], v[134:137]
	v_mfma_f32_16x16x32_bf16 v[134:137], v[86:89], v[102:105], v[170:173]
	v_mfma_f32_16x16x32_bf16 v[170:173], v[98:101], v[114:117], v[134:137]
	v_mfma_f32_16x16x32_bf16 v[134:137], v[18:21], v[118:121], v[158:161]
	v_mfma_f32_16x16x32_bf16 v[158:161], v[82:85], v[130:133], v[134:137]
	v_mfma_f32_16x16x32_bf16 v[134:137], v[86:89], v[118:121], v[154:157]
	v_mfma_f32_16x16x32_bf16 v[154:157], v[98:101], v[130:133], v[134:137]
	v_mfma_f32_16x16x32_bf16 v[134:137], v[18:21], v[178:181], v[142:145]
	v_mfma_f32_16x16x32_bf16 v[142:145], v[82:85], v[190:193], v[134:137]
	v_mfma_f32_16x16x32_bf16 v[134:137], v[86:89], v[178:181], v[138:141]
	v_mfma_f32_16x16x32_bf16 v[126:129], v[18:21], v[200:203], v[126:129]
	v_mfma_f32_16x16x32_bf16 v[122:125], v[86:89], v[200:203], v[122:125]
	v_mfma_f32_16x16x32_bf16 v[138:141], v[98:101], v[190:193], v[134:137]
	v_mfma_f32_16x16x32_bf16 v[126:129], v[82:85], v[222:225], v[126:129]
	v_mfma_f32_16x16x32_bf16 v[122:125], v[98:101], v[222:225], v[122:125]
	s_setprio 0
	s_barrier
	s_add_i32 s44, 0, 0x1c000
	v_add_u32_e32 v134, s44, v204
	s_add_i32 s4, s68, s59
	ds_read_b128 v[226:229], v134
	ds_read_b128 v[230:233], v134 offset:1024
	ds_read_b128 v[234:237], v134 offset:2048
	ds_read_b128 v[238:241], v134 offset:3072
	v_lshl_add_u64 v[134:135], v[210:211], 0, s[22:23]
	s_mov_b32 m0, s4
	s_nop 0
	global_load_lds_dwordx4 v[134:135], off
	v_lshl_add_u64 v[134:135], v[214:215], 0, s[22:23]
	s_add_i32 m0, s4, 0x2000
	s_nop 0
	global_load_lds_dwordx4 v[134:135], off
	s_barrier
	s_waitcnt lgkmcnt(0)
	s_setprio 1
	s_waitcnt lgkmcnt(0)
	v_mfma_f32_16x16x32_bf16 v[38:41], v[234:237], v[102:105], v[38:41]
	v_mfma_f32_16x16x32_bf16 v[162:165], v[238:241], v[114:117], v[38:41]
	v_mfma_f32_16x16x32_bf16 v[38:41], v[226:229], v[118:121], v[42:45]
	v_mfma_f32_16x16x32_bf16 v[150:153], v[230:233], v[130:133], v[38:41]
	v_mfma_f32_16x16x32_bf16 v[38:41], v[234:237], v[118:121], v[46:49]
	v_mfma_f32_16x16x32_bf16 v[134:137], v[226:229], v[102:105], v[166:169]
	v_mfma_f32_16x16x32_bf16 v[146:149], v[238:241], v[130:133], v[38:41]
	v_mfma_f32_16x16x32_bf16 v[38:41], v[226:229], v[178:181], v[54:57]
	v_mfma_f32_16x16x32_bf16 v[166:169], v[230:233], v[114:117], v[134:137]
	v_mfma_f32_16x16x32_bf16 v[134:137], v[230:233], v[190:193], v[38:41]
	v_mfma_f32_16x16x32_bf16 v[38:41], v[234:237], v[178:181], v[58:61]
	v_mfma_f32_16x16x32_bf16 v[130:133], v[238:241], v[190:193], v[38:41]
	v_mfma_f32_16x16x32_bf16 v[38:41], v[226:229], v[200:203], v[62:65]
	v_mfma_f32_16x16x32_bf16 v[118:121], v[230:233], v[222:225], v[38:41]
	v_mfma_f32_16x16x32_bf16 v[38:41], v[234:237], v[200:203], v[66:69]
	v_mfma_f32_16x16x32_bf16 v[114:117], v[238:241], v[222:225], v[38:41]
	s_setprio 0
	s_mov_b32 m0, s64
	v_lshl_add_u64 v[102:103], v[242:243], 0, s[22:23]
	s_barrier
	s_nop 2
	ds_read_b128 v[38:41], v209 offset:49152
	ds_read_b128 v[42:45], v209 offset:50176
	ds_read_b128 v[46:49], v209 offset:51200
	ds_read_b128 v[54:57], v209 offset:52224
	ds_read_b128 v[58:61], v209 offset:53248
	ds_read_b128 v[62:65], v209 offset:54272
	ds_read_b128 v[66:69], v209 offset:55296
	ds_read_b128 v[178:181], v209 offset:56320
	global_load_lds_dwordx4 v[102:103], off
	v_lshl_add_u64 v[102:103], v[244:245], 0, s[22:23]
	s_mov_b32 m0, s65
	s_nop 0
	global_load_lds_dwordx4 v[102:103], off
	s_barrier
	s_waitcnt lgkmcnt(0)
	s_setprio 1
	s_waitcnt lgkmcnt(0)
	v_mfma_f32_16x16x32_bf16 v[102:105], v[18:21], v[38:41], v[110:113]
	v_mfma_f32_16x16x32_bf16 v[110:113], v[82:85], v[42:45], v[102:105]
	v_mfma_f32_16x16x32_bf16 v[102:105], v[86:89], v[38:41], v[106:109]
	v_mfma_f32_16x16x32_bf16 v[94:97], v[18:21], v[46:49], v[94:97]
	v_mfma_f32_16x16x32_bf16 v[90:93], v[86:89], v[46:49], v[90:93]
	v_mfma_f32_16x16x32_bf16 v[78:81], v[18:21], v[58:61], v[78:81]
	v_mfma_f32_16x16x32_bf16 v[74:77], v[86:89], v[58:61], v[74:77]
	v_mfma_f32_16x16x32_bf16 v[14:17], v[18:21], v[66:69], v[14:17]
	v_mfma_f32_16x16x32_bf16 v[10:13], v[86:89], v[66:69], v[10:13]
	v_mfma_f32_16x16x32_bf16 v[106:109], v[98:101], v[42:45], v[102:105]
	v_mfma_f32_16x16x32_bf16 v[94:97], v[82:85], v[54:57], v[94:97]
	v_mfma_f32_16x16x32_bf16 v[90:93], v[98:101], v[54:57], v[90:93]
	v_mfma_f32_16x16x32_bf16 v[78:81], v[82:85], v[62:65], v[78:81]
	v_mfma_f32_16x16x32_bf16 v[74:77], v[98:101], v[62:65], v[74:77]
	v_mfma_f32_16x16x32_bf16 v[18:21], v[82:85], v[178:181], v[14:17]
	v_mfma_f32_16x16x32_bf16 v[10:13], v[98:101], v[178:181], v[10:13]
	s_setprio 0
	s_barrier
	s_add_u32 s4, s42, 0x40080
	s_addc_u32 s5, s43, 0
	s_add_i32 s42, s44, s59
	v_lshl_add_u64 v[14:15], s[4:5], 0, v[184:185]
	s_mov_b32 m0, s42
	s_nop 0
	global_load_lds_dwordx4 v[14:15], off
	v_lshl_add_u64 v[14:15], s[4:5], 0, v[182:183]
	s_add_i32 m0, s42, 0x2000
	s_nop 0
	global_load_lds_dwordx4 v[14:15], off
	s_waitcnt vmcnt(6)
	s_barrier
	s_setprio 1
	v_mfma_f32_16x16x32_bf16 v[14:17], v[226:229], v[38:41], v[22:25]
	v_mfma_f32_16x16x32_bf16 v[102:105], v[230:233], v[42:45], v[14:17]
	v_mfma_f32_16x16x32_bf16 v[14:17], v[234:237], v[38:41], v[26:29]
	v_mfma_f32_16x16x32_bf16 v[98:101], v[238:241], v[42:45], v[14:17]
	v_mfma_f32_16x16x32_bf16 v[14:17], v[226:229], v[46:49], v[30:33]
	v_mfma_f32_16x16x32_bf16 v[86:89], v[230:233], v[54:57], v[14:17]
	v_mfma_f32_16x16x32_bf16 v[14:17], v[234:237], v[46:49], v[70:73]
	v_mfma_f32_16x16x32_bf16 v[82:85], v[238:241], v[54:57], v[14:17]
	v_mfma_f32_16x16x32_bf16 v[14:17], v[226:229], v[58:61], v[50:53]
	v_mfma_f32_16x16x32_bf16 v[50:53], v[230:233], v[62:65], v[14:17]
	v_mfma_f32_16x16x32_bf16 v[14:17], v[234:237], v[58:61], v[34:37]
	v_mfma_f32_16x16x32_bf16 v[6:9], v[226:229], v[66:69], v[6:9]
	v_mfma_f32_16x16x32_bf16 v[2:5], v[234:237], v[66:69], v[2:5]
	v_mfma_f32_16x16x32_bf16 v[34:37], v[238:241], v[62:65], v[14:17]
	v_mfma_f32_16x16x32_bf16 v[6:9], v[230:233], v[178:181], v[6:9]
	v_mfma_f32_16x16x32_bf16 v[2:5], v[238:241], v[178:181], v[2:5]
	s_setprio 0
	s_add_i32 s57, s57, 2
	s_add_u32 s55, s55, 0x100
	s_addc_u32 s56, s56, 0
	s_cmp_gt_u32 s57, 13
	s_mov_b64 s[4:5], s[36:37]
	s_barrier

.Lepi0_seg0:
	v_lshl_or_b32 v202, s27, 8, v208
	s_and_b32 s4, s27, -4
	v_ashrrev_i32_e32 v203, 31, v202
	v_lshlrev_b64 v[14:15], 2, v[202:203]
	v_lshl_add_u64 v[16:17], s[10:11], 0, v[14:15]
	v_lshl_add_u64 v[22:23], s[12:13], 0, v[14:15]
	v_lshlrev_b32_e32 v250, 2, v208
	v_add_u32_e32 v250, 0x20840, v250
	ds_read_b128 v[70:73], v250
	ds_read_b128 v[66:69], v250 offset:1024
	s_cmp_eq_u32 s4, 4
	s_cselect_b64 s[36:37], -1, 0
	s_cmp_lg_u32 s4, 4
	v_mov_b32_e32 v46, 0
	v_and_b32_e32 v210, 0x3ff, v202
	v_mov_b32_e32 v62, 0
	v_mov_b32_e32 v63, 0
	v_mov_b32_e32 v64, 0
	v_mov_b32_e32 v65, 0
	ds_read_b128 v[58:61], v250 offset:16
	ds_read_b128 v[54:57], v250 offset:1040
	v_cndmask_b32_e64 v14, 0, 1, s[36:37]
	v_cmp_ne_u32_e64 s[4:5], 1, v14
	s_andn2_b64 vcc, exec, s[36:37]
	v_mov_b32_e32 v47, 0
	v_mov_b32_e32 v48, 0
	v_mov_b32_e32 v49, 0
	ds_read_b128 v[42:45], v250 offset:512
	ds_read_b128 v[38:41], v250 offset:1536
	v_add_u32_e32 v212, 0x80, v202
	v_mov_b32_e32 v14, 0
	s_and_b64 vcc, exec, s[4:5]
	v_and_b32_e32 v203, 0x3ff, v212
	v_mov_b32_e32 v30, 0
	v_mov_b32_e32 v31, 0
	v_mov_b32_e32 v32, 0
	v_mov_b32_e32 v33, 0
	ds_read_b128 v[26:29], v250 offset:528
	s_nop 0
	ds_read_b128 v[22:25], v250 offset:1552
	s_and_b64 vcc, exec, s[4:5]
	v_mov_b32_e32 v15, 0
	v_mov_b32_e32 v16, 0
	v_mov_b32_e32 v17, 0
	v_mov_b32_e32 v214, v1
	v_cndmask_b32_e64 v178, 0, 1, s[6:7]
	v_cmp_ne_u32_e64 s[46:47], 1, v178
	s_andn2_b64 vcc, exec, s[6:7]
	v_lshl_add_u32 v211, v214, 3, s33
	s_cbranch_vccnz .LBB0_407_sg0
	ds_read_b64 v[200:201], v211
	s_waitcnt lgkmcnt(0)
	v_mov_b32_e32 v192, v201
	s_branch .LBB0_408_sg0

.LBB0_408_sg0:
	s_waitcnt lgkmcnt(0)
	v_xor_b32_e32 v191, 0x80000000, v73
	v_xor_b32_e32 v190, 0x80000000, v72
	v_pk_fma_f32 v[72:73], v[190:191], v[200:201], v[176:177] op_sel_hi:[1,0,1]
	v_pk_fma_f32 v[174:175], v[70:71], v[200:201], v[174:175] op_sel_hi:[1,0,1] neg_lo:[1,0,0] neg_hi:[1,0,0]
	s_movk_i32 s4, 0x3ff
	v_pk_fma_f32 v[174:175], v[192:193], v[174:175], v[66:67] op_sel_hi:[0,1,1]
	v_pk_fma_f32 v[176:177], v[192:193], v[72:73], v[68:69] op_sel_hi:[0,1,1]
	v_cmp_lt_u32_e64 s[42:43], s4, v202
	s_and_saveexec_b64 s[4:5], s[42:43]
	s_xor_b64 s[4:5], exec, s[4:5]
	s_andn2_saveexec_b64 s[4:5], s[4:5]
	v_mul_f32_e32 v72, 0xbfb8aa3b, v174
	v_mul_f32_e32 v73, 0xbfb8aa3b, v175
	v_mul_f32_e32 v178, 0xbfb8aa3b, v176
	v_mul_f32_e32 v179, 0xbfb8aa3b, v177
	v_exp_f32_e32 v72, v72
	v_exp_f32_e32 v73, v73
	v_exp_f32_e32 v178, v178
	v_exp_f32_e32 v179, v179
	v_add_f32_e32 v72, 1.0, v72
	v_add_f32_e32 v73, 1.0, v73
	v_add_f32_e32 v178, 1.0, v178
	v_add_f32_e32 v179, 1.0, v179
	v_rcp_f32_e32 v72, v72
	v_rcp_f32_e32 v73, v73
	v_rcp_f32_e32 v178, v178
	v_rcp_f32_e32 v179, v179
	s_mov_b32 s36, 0x3db504f3
	v_pk_mul_f32 v[72:73], v[174:175], v[72:73]
	v_pk_mul_f32 v[174:175], v[176:177], v[178:179]
	s_nop 0
	v_pk_mul_f32 v[180:181], v[174:175], s[36:37] op_sel_hi:[1,0]
	v_pk_mul_f32 v[178:179], v[72:73], s[36:37] op_sel_hi:[1,0]
	s_or_b64 exec, exec, s[4:5]
	v_mov_b32_e32 v201, v200
	v_xor_b32_e32 v61, 0x80000000, v61
	v_xor_b32_e32 v60, 0x80000000, v60
	v_mov_b32_e32 v72, v200
	v_mov_b32_e32 v73, v200
	v_mov_b32_e32 v193, v192
	v_pk_fma_f32 v[72:73], v[60:61], v[72:73], v[172:173]
	v_pk_fma_f32 v[170:171], v[58:59], v[200:201], v[170:171] neg_lo:[1,0,0] neg_hi:[1,0,0]
	v_mov_b32_e32 v172, v192
	v_mov_b32_e32 v173, v192
	v_pk_fma_f32 v[170:171], v[192:193], v[170:171], v[54:55]
	v_pk_fma_f32 v[172:173], v[172:173], v[72:73], v[56:57]
	v_cvt_pk_bf16_f32 v174, v178, v179
	v_cvt_pk_bf16_f32 v175, v180, v181
	s_and_saveexec_b64 s[4:5], s[42:43]
	s_xor_b64 s[4:5], exec, s[4:5]
	s_andn2_saveexec_b64 s[4:5], s[4:5]
	v_mul_f32_e32 v72, 0xbfb8aa3b, v170
	v_mul_f32_e32 v73, 0xbfb8aa3b, v171
	v_mul_f32_e32 v176, 0xbfb8aa3b, v172
	v_mul_f32_e32 v177, 0xbfb8aa3b, v173
	v_exp_f32_e32 v72, v72
	v_exp_f32_e32 v73, v73
	v_exp_f32_e32 v176, v176
	v_exp_f32_e32 v177, v177
	v_add_f32_e32 v72, 1.0, v72
	v_add_f32_e32 v73, 1.0, v73
	v_add_f32_e32 v176, 1.0, v176
	v_add_f32_e32 v177, 1.0, v177
	v_rcp_f32_e32 v72, v72
	v_rcp_f32_e32 v73, v73
	v_rcp_f32_e32 v176, v176
	v_rcp_f32_e32 v177, v177
	s_mov_b32 s36, 0x3db504f3
	v_pk_mul_f32 v[72:73], v[170:171], v[72:73]
	v_mov_b32_e32 v180, 0
	v_pk_mul_f32 v[170:171], v[172:173], v[176:177]
	v_pk_mul_f32 v[176:177], v[72:73], s[36:37] op_sel_hi:[1,0]
	v_pk_mul_f32 v[178:179], v[170:171], s[36:37] op_sel_hi:[1,0]
	s_or_b64 exec, exec, s[4:5]
	s_lshl_b32 s51, s3, 8
	v_add_lshl_u32 v181, v214, s51, 10
	s_mov_b32 s3, 0x1020000
	v_cvt_pk_bf16_f32 v176, v176, v177
	v_cvt_pk_bf16_f32 v177, v178, v179
	v_mul_lo_u32 v178, v180, s3
	v_or_b32_e32 v72, v181, v210
	v_add_lshl_u32 v72, v72, v178, 1
	buffer_store_dwordx4 v[174:177], v72, s[28:31], 0 offen sc1
	v_xor_b32_e32 v45, 0x80000000, v45
	v_xor_b32_e32 v44, 0x80000000, v44
	v_mov_b32_e32 v72, v200
	v_mov_b32_e32 v73, v200
	v_pk_fma_f32 v[72:73], v[44:45], v[72:73], v[168:169]
	v_pk_fma_f32 v[166:167], v[42:43], v[200:201], v[166:167] neg_lo:[1,0,0] neg_hi:[1,0,0]
	v_mov_b32_e32 v168, v192
	v_mov_b32_e32 v169, v192
	s_movk_i32 s3, 0x3ff
	v_pk_fma_f32 v[166:167], v[192:193], v[166:167], v[38:39]
	v_pk_fma_f32 v[168:169], v[168:169], v[72:73], v[40:41]
	v_cmp_lt_u32_e64 s[44:45], s3, v212
	s_and_saveexec_b64 s[4:5], s[44:45]
	s_xor_b64 s[4:5], exec, s[4:5]
	s_andn2_saveexec_b64 s[4:5], s[4:5]
	v_mul_f32_e32 v72, 0xbfb8aa3b, v166
	v_mul_f32_e32 v73, 0xbfb8aa3b, v167
	v_mul_f32_e32 v170, 0xbfb8aa3b, v168
	v_mul_f32_e32 v171, 0xbfb8aa3b, v169
	v_exp_f32_e32 v72, v72
	v_exp_f32_e32 v73, v73
	v_exp_f32_e32 v170, v170
	v_exp_f32_e32 v171, v171
	v_add_f32_e32 v72, 1.0, v72
	v_add_f32_e32 v73, 1.0, v73
	v_add_f32_e32 v170, 1.0, v170
	v_add_f32_e32 v171, 1.0, v171
	v_rcp_f32_e32 v72, v72
	v_rcp_f32_e32 v73, v73
	v_rcp_f32_e32 v170, v170
	v_rcp_f32_e32 v171, v171
	s_mov_b32 s36, 0x3db504f3
	v_pk_mul_f32 v[72:73], v[166:167], v[72:73]
	v_pk_mul_f32 v[166:167], v[168:169], v[170:171]
	s_nop 0
	v_pk_mul_f32 v[172:173], v[166:167], s[36:37] op_sel_hi:[1,0]
	v_pk_mul_f32 v[170:171], v[72:73], s[36:37] op_sel_hi:[1,0]
	s_or_b64 exec, exec, s[4:5]
	v_xor_b32_e32 v29, 0x80000000, v29
	v_xor_b32_e32 v28, 0x80000000, v28
	v_mov_b32_e32 v72, v200
	v_mov_b32_e32 v73, v200
	v_pk_fma_f32 v[162:163], v[26:27], v[200:201], v[162:163] neg_lo:[1,0,0] neg_hi:[1,0,0]
	v_pk_fma_f32 v[72:73], v[28:29], v[72:73], v[164:165]
	v_pk_fma_f32 v[162:163], v[192:193], v[162:163], v[22:23]
	v_mov_b32_e32 v193, v192
	v_pk_fma_f32 v[164:165], v[192:193], v[72:73], v[24:25]
	v_cvt_pk_bf16_f32 v166, v170, v171
	v_cvt_pk_bf16_f32 v167, v172, v173
	s_and_saveexec_b64 s[4:5], s[44:45]
	s_xor_b64 s[4:5], exec, s[4:5]
	s_andn2_saveexec_b64 s[4:5], s[4:5]
	v_mul_f32_e32 v72, 0xbfb8aa3b, v162
	v_mul_f32_e32 v73, 0xbfb8aa3b, v163
	v_mul_f32_e32 v168, 0xbfb8aa3b, v164
	v_mul_f32_e32 v169, 0xbfb8aa3b, v165
	v_exp_f32_e32 v72, v72
	v_exp_f32_e32 v73, v73
	v_exp_f32_e32 v168, v168
	v_exp_f32_e32 v169, v169
	v_add_f32_e32 v72, 1.0, v72
	v_add_f32_e32 v73, 1.0, v73
	v_add_f32_e32 v168, 1.0, v168
	v_add_f32_e32 v169, 1.0, v169
	v_rcp_f32_e32 v72, v72
	v_rcp_f32_e32 v73, v73
	v_rcp_f32_e32 v168, v168
	v_rcp_f32_e32 v169, v169
	s_mov_b32 s36, 0x3db504f3
	v_pk_mul_f32 v[72:73], v[162:163], v[72:73]
	v_mov_b32_e32 v172, 0
	v_pk_mul_f32 v[162:163], v[164:165], v[168:169]
	v_pk_mul_f32 v[168:169], v[72:73], s[36:37] op_sel_hi:[1,0]
	v_pk_mul_f32 v[170:171], v[162:163], s[36:37] op_sel_hi:[1,0]
	s_or_b64 exec, exec, s[4:5]
	s_mov_b32 s3, 0x1020000
	v_cvt_pk_bf16_f32 v168, v168, v169
	v_cvt_pk_bf16_f32 v169, v170, v171
	v_mul_lo_u32 v170, v172, s3
	v_or_b32_e32 v72, v181, v203
	v_add_lshl_u32 v72, v72, v170, 1
	s_and_b64 vcc, exec, s[46:47]
	buffer_store_dwordx4 v[166:169], v72, s[28:31], 0 offen sc1
	s_cbranch_vccnz .LBB0_458_sg0
	ds_read_b64 v[166:167], v211 offset:128
	s_waitcnt lgkmcnt(0)
	v_mov_b32_e32 v72, v167
	s_branch .LBB0_459_sg0

.Lepi0_seg1:
	v_lshl_or_b32 v202, s27, 8, v208
	s_and_b32 s4, s27, -4
	v_ashrrev_i32_e32 v203, 31, v202
	v_lshlrev_b64 v[14:15], 2, v[202:203]
	v_lshl_add_u64 v[16:17], s[10:11], 0, v[14:15]
	v_lshl_add_u64 v[22:23], s[12:13], 0, v[14:15]
	v_lshlrev_b32_e32 v250, 2, v208
	v_add_u32_e32 v250, 0x20840, v250
	ds_read_b128 v[70:73], v250
	ds_read_b128 v[66:69], v250 offset:1024
	s_cmp_eq_u32 s4, 4
	s_cselect_b64 s[36:37], -1, 0
	s_cmp_lg_u32 s4, 4
	v_mov_b32_e32 v46, 0
	v_and_b32_e32 v210, 0x3ff, v202
	v_mov_b32_e32 v62, 0
	v_mov_b32_e32 v63, 0
	v_mov_b32_e32 v64, 0
	v_mov_b32_e32 v65, 0
	v_lshlrev_b32_e32 v14, 2, v210
	v_mov_b32_e32 v15, v0
	v_lshl_add_u64 v[14:15], s[14:15], 0, v[14:15]
	ds_read_b128 v[62:65], v250 offset:2048
	ds_read_b128 v[58:61], v250 offset:16
	ds_read_b128 v[54:57], v250 offset:1040
	v_cndmask_b32_e64 v14, 0, 1, s[36:37]
	v_cmp_ne_u32_e64 s[4:5], 1, v14
	s_andn2_b64 vcc, exec, s[36:37]
	v_mov_b32_e32 v47, 0
	v_mov_b32_e32 v48, 0
	v_mov_b32_e32 v49, 0
	v_add_u32_e32 v14, 4, v202
	v_and_b32_e32 v14, 0x3ff, v14
	v_lshlrev_b32_e32 v14, 2, v14
	v_mov_b32_e32 v15, v0
	v_lshl_add_u64 v[14:15], s[14:15], 0, v[14:15]
	ds_read_b128 v[46:49], v250 offset:2064
	ds_read_b128 v[42:45], v250 offset:512
	ds_read_b128 v[38:41], v250 offset:1536
	v_add_u32_e32 v212, 0x80, v202
	v_mov_b32_e32 v14, 0
	s_and_b64 vcc, exec, s[4:5]
	v_and_b32_e32 v203, 0x3ff, v212
	v_mov_b32_e32 v30, 0
	v_mov_b32_e32 v31, 0
	v_mov_b32_e32 v32, 0
	v_mov_b32_e32 v33, 0
	v_lshlrev_b32_e32 v24, 2, v203
	v_mov_b32_e32 v25, v0
	v_lshl_add_u64 v[24:25], s[14:15], 0, v[24:25]
	ds_read_b128 v[30:33], v250 offset:2560
	ds_read_b128 v[26:29], v250 offset:528
	s_nop 0
	ds_read_b128 v[22:25], v250 offset:1552
	s_and_b64 vcc, exec, s[4:5]
	v_mov_b32_e32 v15, 0
	v_mov_b32_e32 v16, 0
	v_mov_b32_e32 v17, 0
	v_add_u32_e32 v14, 0x84, v202
	v_and_b32_e32 v14, 0x3ff, v14
	v_lshlrev_b32_e32 v14, 2, v14
	v_mov_b32_e32 v15, v0
	v_lshl_add_u64 v[14:15], s[14:15], 0, v[14:15]
	ds_read_b128 v[14:17], v250 offset:2576
	v_mov_b32_e32 v214, v1
	v_cndmask_b32_e64 v178, 0, 1, s[6:7]
	v_cmp_ne_u32_e64 s[46:47], 1, v178
	s_andn2_b64 vcc, exec, s[6:7]
	v_lshl_add_u32 v211, v214, 3, s33
	s_cbranch_vccnz .LBB0_407_sg1
	ds_read_b64 v[200:201], v211
	s_waitcnt lgkmcnt(0)
	v_mov_b32_e32 v192, v201
	s_branch .LBB0_408_sg1

.LBB0_408_sg1:
	s_waitcnt lgkmcnt(0)
	v_xor_b32_e32 v191, 0x80000000, v73
	v_xor_b32_e32 v190, 0x80000000, v72
	v_pk_fma_f32 v[72:73], v[190:191], v[200:201], v[176:177] op_sel_hi:[1,0,1]
	v_pk_fma_f32 v[174:175], v[70:71], v[200:201], v[174:175] op_sel_hi:[1,0,1] neg_lo:[1,0,0] neg_hi:[1,0,0]
	s_movk_i32 s4, 0x3ff
	v_pk_fma_f32 v[174:175], v[192:193], v[174:175], v[66:67] op_sel_hi:[0,1,1]
	v_pk_fma_f32 v[176:177], v[192:193], v[72:73], v[68:69] op_sel_hi:[0,1,1]
	v_cmp_lt_u32_e64 s[42:43], s4, v202
	s_and_saveexec_b64 s[4:5], s[42:43]
	s_xor_b64 s[4:5], exec, s[4:5]
	v_ashrrev_i32_e32 v72, 10, v202
	v_cmp_lt_i32_e32 vcc, 1, v72
	s_mov_b64 s[36:37], 0
	s_mov_b64 s[44:45], 0
	s_and_saveexec_b64 s[54:55], vcc
	s_xor_b64 s[54:55], exec, s[54:55]
	v_cmp_ne_u32_e32 vcc, 2, v72
	s_and_b64 s[44:45], vcc, exec
	s_andn2_saveexec_b64 s[54:55], s[54:55]
	v_cmp_ne_u32_e32 vcc, 1, v72
	s_andn2_b64 s[36:37], s[44:45], exec
	s_and_b64 s[44:45], vcc, exec
	s_or_b64 s[44:45], s[36:37], s[44:45]
	s_mov_b64 s[36:37], exec
	s_or_b64 exec, exec, s[54:55]
	v_mov_b64_e32 v[180:181], v[176:177]
	v_mov_b64_e32 v[178:179], v[174:175]
	s_and_saveexec_b64 s[54:55], s[44:45]
	s_xor_b64 s[44:45], exec, s[54:55]
	s_or_b64 exec, exec, s[44:45]
	s_and_saveexec_b64 s[44:45], s[36:37]
	s_mov_b32 s27, 0xbfb8aa3b
	v_mul_f32_e64 v72, -v174, s27
	v_mul_f32_e64 v175, -v175, s27
	v_mul_f32_e64 v176, -v176, s27
	v_mul_f32_e64 v177, -v177, s27
	v_exp_f32_e32 v174, v72
	v_exp_f32_e32 v175, v175
	v_exp_f32_e32 v176, v176
	v_exp_f32_e32 v177, v177
	v_add_f32_e32 v174, 1.0, v174
	v_add_f32_e32 v175, 1.0, v175
	v_add_f32_e32 v176, 1.0, v176
	v_add_f32_e32 v177, 1.0, v177
	v_rcp_f32_e32 v174, v174
	v_rcp_f32_e32 v176, v176
	v_rcp_f32_e32 v177, v177
	v_rcp_f32_e32 v175, v175
	v_sub_f32_e32 v73, 1.0, v63
	v_sub_f32_e32 v72, 1.0, v62
	v_sub_f32_e32 v179, 1.0, v65
	v_sub_f32_e32 v178, 1.0, v64
	v_pk_mul_f32 v[180:181], v[178:179], v[176:177]
	v_pk_mul_f32 v[178:179], v[72:73], v[174:175]
	s_or_b64 exec, exec, s[44:45]
	s_andn2_saveexec_b64 s[4:5], s[4:5]
	s_or_b64 exec, exec, s[4:5]
	v_mov_b32_e32 v201, v200
	v_xor_b32_e32 v61, 0x80000000, v61
	v_xor_b32_e32 v60, 0x80000000, v60
	v_mov_b32_e32 v72, v200
	v_mov_b32_e32 v73, v200
	v_mov_b32_e32 v193, v192
	v_pk_fma_f32 v[72:73], v[60:61], v[72:73], v[172:173]
	v_pk_fma_f32 v[170:171], v[58:59], v[200:201], v[170:171] neg_lo:[1,0,0] neg_hi:[1,0,0]
	v_mov_b32_e32 v172, v192
	v_mov_b32_e32 v173, v192
	v_pk_fma_f32 v[170:171], v[192:193], v[170:171], v[54:55]
	v_pk_fma_f32 v[172:173], v[172:173], v[72:73], v[56:57]
	v_cvt_pk_bf16_f32 v174, v178, v179
	v_cvt_pk_bf16_f32 v175, v180, v181
	s_and_saveexec_b64 s[4:5], s[42:43]
	s_xor_b64 s[4:5], exec, s[4:5]
	v_ashrrev_i32_e32 v180, 10, v202
	v_cmp_lt_i32_e32 vcc, 1, v180
	s_mov_b64 s[36:37], 0
	s_mov_b64 s[44:45], 0
	s_and_saveexec_b64 s[54:55], vcc
	s_xor_b64 s[54:55], exec, s[54:55]
	v_cmp_ne_u32_e32 vcc, 2, v180
	s_and_b64 s[44:45], vcc, exec
	s_andn2_saveexec_b64 s[54:55], s[54:55]
	v_cmp_ne_u32_e32 vcc, 1, v180
	s_andn2_b64 s[36:37], s[44:45], exec
	s_and_b64 s[44:45], vcc, exec
	s_or_b64 s[44:45], s[36:37], s[44:45]
	s_mov_b64 s[36:37], exec
	s_or_b64 exec, exec, s[54:55]
	v_mov_b64_e32 v[178:179], v[172:173]
	v_mov_b64_e32 v[176:177], v[170:171]
	s_and_saveexec_b64 s[54:55], s[44:45]
	s_xor_b64 s[44:45], exec, s[54:55]
	s_or_b64 exec, exec, s[44:45]
	s_and_saveexec_b64 s[44:45], s[36:37]
	s_mov_b32 s27, 0xbfb8aa3b
	v_mul_f32_e64 v72, -v170, s27
	v_mul_f32_e64 v171, -v171, s27
	v_mul_f32_e64 v172, -v172, s27
	v_mul_f32_e64 v173, -v173, s27
	v_exp_f32_e32 v170, v72
	v_exp_f32_e32 v171, v171
	v_exp_f32_e32 v172, v172
	v_exp_f32_e32 v173, v173
	v_add_f32_e32 v170, 1.0, v170
	v_add_f32_e32 v171, 1.0, v171
	v_add_f32_e32 v172, 1.0, v172
	v_add_f32_e32 v173, 1.0, v173
	v_rcp_f32_e32 v170, v170
	v_rcp_f32_e32 v172, v172
	v_rcp_f32_e32 v173, v173
	v_rcp_f32_e32 v171, v171
	v_sub_f32_e32 v73, 1.0, v47
	v_sub_f32_e32 v72, 1.0, v46
	v_sub_f32_e32 v177, 1.0, v49
	v_sub_f32_e32 v176, 1.0, v48
	v_pk_mul_f32 v[178:179], v[176:177], v[172:173]
	v_pk_mul_f32 v[176:177], v[72:73], v[170:171]
	v_mov_b32_e32 v180, 1
	s_or_b64 exec, exec, s[44:45]
	s_andn2_saveexec_b64 s[4:5], s[4:5]
	s_or_b64 exec, exec, s[4:5]
	s_lshl_b32 s51, s3, 8
	v_add_lshl_u32 v181, v214, s51, 10
	s_mov_b32 s3, 0x1020000
	v_cvt_pk_bf16_f32 v176, v176, v177
	v_cvt_pk_bf16_f32 v177, v178, v179
	v_mul_lo_u32 v178, v180, s3
	v_or_b32_e32 v72, v181, v210
	v_add_lshl_u32 v72, v72, v178, 1
	buffer_store_dwordx4 v[174:177], v72, s[28:31], 0 offen sc1
	v_xor_b32_e32 v45, 0x80000000, v45
	v_xor_b32_e32 v44, 0x80000000, v44
	v_mov_b32_e32 v72, v200
	v_mov_b32_e32 v73, v200
	v_pk_fma_f32 v[72:73], v[44:45], v[72:73], v[168:169]
	v_pk_fma_f32 v[166:167], v[42:43], v[200:201], v[166:167] neg_lo:[1,0,0] neg_hi:[1,0,0]
	v_mov_b32_e32 v168, v192
	v_mov_b32_e32 v169, v192
	s_movk_i32 s3, 0x3ff
	v_pk_fma_f32 v[166:167], v[192:193], v[166:167], v[38:39]
	v_pk_fma_f32 v[168:169], v[168:169], v[72:73], v[40:41]
	v_cmp_lt_u32_e64 s[44:45], s3, v212
	s_and_saveexec_b64 s[4:5], s[44:45]
	s_xor_b64 s[4:5], exec, s[4:5]
	v_ashrrev_i32_e32 v72, 10, v212
	v_cmp_lt_i32_e32 vcc, 1, v72
	s_mov_b64 s[36:37], 0
	s_mov_b64 s[54:55], 0
	s_and_saveexec_b64 s[56:57], vcc
	s_xor_b64 s[56:57], exec, s[56:57]
	v_cmp_ne_u32_e32 vcc, 2, v72
	s_and_b64 s[54:55], vcc, exec
	s_andn2_saveexec_b64 s[56:57], s[56:57]
	v_cmp_ne_u32_e32 vcc, 1, v72
	s_andn2_b64 s[36:37], s[54:55], exec
	s_and_b64 s[54:55], vcc, exec
	s_or_b64 s[54:55], s[36:37], s[54:55]
	s_mov_b64 s[36:37], exec
	s_or_b64 exec, exec, s[56:57]
	v_mov_b64_e32 v[172:173], v[168:169]
	v_mov_b64_e32 v[170:171], v[166:167]
	s_and_saveexec_b64 s[56:57], s[54:55]
	s_xor_b64 s[54:55], exec, s[56:57]
	s_or_b64 exec, exec, s[54:55]
	s_and_saveexec_b64 s[54:55], s[36:37]
	s_mov_b32 s3, 0xbfb8aa3b
	v_mul_f32_e64 v72, -v166, s3
	v_mul_f32_e64 v167, -v167, s3
	v_mul_f32_e64 v168, -v168, s3
	v_mul_f32_e64 v169, -v169, s3
	v_exp_f32_e32 v166, v72
	v_exp_f32_e32 v167, v167
	v_exp_f32_e32 v168, v168
	v_exp_f32_e32 v169, v169
	v_add_f32_e32 v166, 1.0, v166
	v_add_f32_e32 v167, 1.0, v167
	v_add_f32_e32 v168, 1.0, v168
	v_add_f32_e32 v169, 1.0, v169
	v_rcp_f32_e32 v166, v166
	v_rcp_f32_e32 v168, v168
	v_rcp_f32_e32 v169, v169
	v_rcp_f32_e32 v167, v167
	v_sub_f32_e32 v73, 1.0, v31
	v_sub_f32_e32 v72, 1.0, v30
	v_sub_f32_e32 v171, 1.0, v33
	v_sub_f32_e32 v170, 1.0, v32
	v_pk_mul_f32 v[172:173], v[170:171], v[168:169]
	v_pk_mul_f32 v[170:171], v[72:73], v[166:167]
	s_or_b64 exec, exec, s[54:55]
	s_andn2_saveexec_b64 s[4:5], s[4:5]
	s_or_b64 exec, exec, s[4:5]
	v_xor_b32_e32 v29, 0x80000000, v29
	v_xor_b32_e32 v28, 0x80000000, v28
	v_mov_b32_e32 v72, v200
	v_mov_b32_e32 v73, v200
	v_pk_fma_f32 v[162:163], v[26:27], v[200:201], v[162:163] neg_lo:[1,0,0] neg_hi:[1,0,0]
	v_pk_fma_f32 v[72:73], v[28:29], v[72:73], v[164:165]
	v_pk_fma_f32 v[162:163], v[192:193], v[162:163], v[22:23]
	v_mov_b32_e32 v193, v192
	v_pk_fma_f32 v[164:165], v[192:193], v[72:73], v[24:25]
	v_cvt_pk_bf16_f32 v166, v170, v171
	v_cvt_pk_bf16_f32 v167, v172, v173
	s_and_saveexec_b64 s[4:5], s[44:45]
	s_xor_b64 s[4:5], exec, s[4:5]
	v_ashrrev_i32_e32 v172, 10, v212
	v_cmp_lt_i32_e32 vcc, 1, v172
	s_mov_b64 s[36:37], 0
	s_mov_b64 s[54:55], 0
	s_and_saveexec_b64 s[56:57], vcc
	s_xor_b64 s[56:57], exec, s[56:57]
	v_cmp_ne_u32_e32 vcc, 2, v172
	s_and_b64 s[54:55], vcc, exec
	s_andn2_saveexec_b64 s[56:57], s[56:57]
	v_cmp_ne_u32_e32 vcc, 1, v172
	s_andn2_b64 s[36:37], s[54:55], exec
	s_and_b64 s[54:55], vcc, exec
	s_or_b64 s[54:55], s[36:37], s[54:55]
	s_mov_b64 s[36:37], exec
	s_or_b64 exec, exec, s[56:57]
	v_mov_b64_e32 v[170:171], v[164:165]
	v_mov_b64_e32 v[168:169], v[162:163]
	s_and_saveexec_b64 s[56:57], s[54:55]
	s_xor_b64 s[54:55], exec, s[56:57]
	s_or_b64 exec, exec, s[54:55]
	s_and_saveexec_b64 s[54:55], s[36:37]
	s_mov_b32 s3, 0xbfb8aa3b
	v_mul_f32_e64 v72, -v162, s3
	v_mul_f32_e64 v163, -v163, s3
	v_mul_f32_e64 v164, -v164, s3
	v_mul_f32_e64 v165, -v165, s3
	v_exp_f32_e32 v162, v72
	v_exp_f32_e32 v163, v163
	v_exp_f32_e32 v164, v164
	v_exp_f32_e32 v165, v165
	v_add_f32_e32 v162, 1.0, v162
	v_add_f32_e32 v163, 1.0, v163
	v_add_f32_e32 v164, 1.0, v164
	v_add_f32_e32 v165, 1.0, v165
	v_rcp_f32_e32 v162, v162
	v_rcp_f32_e32 v164, v164
	v_rcp_f32_e32 v165, v165
	v_rcp_f32_e32 v163, v163
	v_sub_f32_e32 v73, 1.0, v15
	v_sub_f32_e32 v72, 1.0, v14
	v_sub_f32_e32 v169, 1.0, v17
	v_sub_f32_e32 v168, 1.0, v16
	v_pk_mul_f32 v[170:171], v[168:169], v[164:165]
	v_pk_mul_f32 v[168:169], v[72:73], v[162:163]
	v_mov_b32_e32 v172, 1
	s_or_b64 exec, exec, s[54:55]
	s_andn2_saveexec_b64 s[4:5], s[4:5]
	s_or_b64 exec, exec, s[4:5]
	s_mov_b32 s3, 0x1020000
	v_cvt_pk_bf16_f32 v168, v168, v169
	v_cvt_pk_bf16_f32 v169, v170, v171
	v_mul_lo_u32 v170, v172, s3
	v_or_b32_e32 v72, v181, v203
	v_add_lshl_u32 v72, v72, v170, 1
	s_and_b64 vcc, exec, s[46:47]
	buffer_store_dwordx4 v[166:169], v72, s[28:31], 0 offen sc1
	s_cbranch_vccnz .LBB0_458_sg1
	ds_read_b64 v[166:167], v211 offset:128
	s_waitcnt lgkmcnt(0)
	v_mov_b32_e32 v72, v167
	s_branch .LBB0_459_sg1

.LBB0_408_sg2:
	s_waitcnt lgkmcnt(0)
	v_xor_b32_e32 v191, 0x80000000, v73
	v_xor_b32_e32 v190, 0x80000000, v72
	v_pk_fma_f32 v[72:73], v[190:191], v[200:201], v[176:177] op_sel_hi:[1,0,1]
	v_pk_fma_f32 v[174:175], v[70:71], v[200:201], v[174:175] op_sel_hi:[1,0,1] neg_lo:[1,0,0] neg_hi:[1,0,0]
	s_movk_i32 s4, 0x3ff
	v_pk_fma_f32 v[174:175], v[192:193], v[174:175], v[66:67] op_sel_hi:[0,1,1]
	v_pk_fma_f32 v[176:177], v[192:193], v[72:73], v[68:69] op_sel_hi:[0,1,1]
	v_cmp_lt_u32_e64 s[42:43], s4, v202
	s_and_saveexec_b64 s[4:5], s[42:43]
	s_xor_b64 s[4:5], exec, s[4:5]
	v_ashrrev_i32_e32 v72, 10, v202
	v_cmp_lt_i32_e32 vcc, 1, v72
	s_mov_b64 s[36:37], 0
	s_mov_b64 s[44:45], 0
	s_and_saveexec_b64 s[54:55], vcc
	s_xor_b64 s[54:55], exec, s[54:55]
	v_cmp_ne_u32_e32 vcc, 2, v72
	s_and_b64 s[44:45], vcc, exec
	s_andn2_saveexec_b64 s[54:55], s[54:55]
	v_cmp_ne_u32_e32 vcc, 1, v72
	s_andn2_b64 s[36:37], s[44:45], exec
	s_and_b64 s[44:45], vcc, exec
	s_or_b64 s[44:45], s[36:37], s[44:45]
	s_mov_b64 s[36:37], exec
	s_or_b64 exec, exec, s[54:55]
	v_mov_b64_e32 v[180:181], v[176:177]
	v_mov_b64_e32 v[178:179], v[174:175]
	s_and_saveexec_b64 s[54:55], s[44:45]
	s_xor_b64 s[44:45], exec, s[54:55]
	s_or_b64 exec, exec, s[44:45]
	s_and_saveexec_b64 s[44:45], s[36:37]
	s_or_b64 exec, exec, s[44:45]
	s_andn2_saveexec_b64 s[4:5], s[4:5]
	s_or_b64 exec, exec, s[4:5]
	v_mov_b32_e32 v201, v200
	v_xor_b32_e32 v61, 0x80000000, v61
	v_xor_b32_e32 v60, 0x80000000, v60
	v_mov_b32_e32 v72, v200
	v_mov_b32_e32 v73, v200
	v_mov_b32_e32 v193, v192
	v_pk_fma_f32 v[72:73], v[60:61], v[72:73], v[172:173]
	v_pk_fma_f32 v[170:171], v[58:59], v[200:201], v[170:171] neg_lo:[1,0,0] neg_hi:[1,0,0]
	v_mov_b32_e32 v172, v192
	v_mov_b32_e32 v173, v192
	v_pk_fma_f32 v[170:171], v[192:193], v[170:171], v[54:55]
	v_pk_fma_f32 v[172:173], v[172:173], v[72:73], v[56:57]
	v_cvt_pk_bf16_f32 v174, v178, v179
	v_cvt_pk_bf16_f32 v175, v180, v181
	s_and_saveexec_b64 s[4:5], s[42:43]
	s_xor_b64 s[4:5], exec, s[4:5]
	v_ashrrev_i32_e32 v180, 10, v202
	v_cmp_lt_i32_e32 vcc, 1, v180
	s_mov_b64 s[36:37], 0
	s_mov_b64 s[44:45], 0
	s_and_saveexec_b64 s[54:55], vcc
	s_xor_b64 s[54:55], exec, s[54:55]
	v_cmp_ne_u32_e32 vcc, 2, v180
	s_and_b64 s[44:45], vcc, exec
	s_andn2_saveexec_b64 s[54:55], s[54:55]
	v_cmp_ne_u32_e32 vcc, 1, v180
	s_andn2_b64 s[36:37], s[44:45], exec
	s_and_b64 s[44:45], vcc, exec
	s_or_b64 s[44:45], s[36:37], s[44:45]
	s_mov_b64 s[36:37], exec
	s_or_b64 exec, exec, s[54:55]
	v_mov_b64_e32 v[178:179], v[172:173]
	v_mov_b64_e32 v[176:177], v[170:171]
	s_and_saveexec_b64 s[54:55], s[44:45]
	s_xor_b64 s[44:45], exec, s[54:55]
	s_or_b64 exec, exec, s[44:45]
	s_and_saveexec_b64 s[44:45], s[36:37]
	s_or_b64 exec, exec, s[44:45]
	s_andn2_saveexec_b64 s[4:5], s[4:5]
	s_or_b64 exec, exec, s[4:5]
	s_lshl_b32 s51, s3, 8
	v_add_lshl_u32 v181, v214, s51, 10
	s_mov_b32 s3, 0x1020000
	v_cvt_pk_bf16_f32 v176, v176, v177
	v_cvt_pk_bf16_f32 v177, v178, v179
	v_mul_lo_u32 v178, v180, s3
	v_or_b32_e32 v72, v181, v210
	v_add_lshl_u32 v72, v72, v178, 1
	buffer_store_dwordx4 v[174:177], v72, s[28:31], 0 offen sc1
	v_xor_b32_e32 v45, 0x80000000, v45
	v_xor_b32_e32 v44, 0x80000000, v44
	v_mov_b32_e32 v72, v200
	v_mov_b32_e32 v73, v200
	v_pk_fma_f32 v[72:73], v[44:45], v[72:73], v[168:169]
	v_pk_fma_f32 v[166:167], v[42:43], v[200:201], v[166:167] neg_lo:[1,0,0] neg_hi:[1,0,0]
	v_mov_b32_e32 v168, v192
	v_mov_b32_e32 v169, v192
	s_movk_i32 s3, 0x3ff
	v_pk_fma_f32 v[166:167], v[192:193], v[166:167], v[38:39]
	v_pk_fma_f32 v[168:169], v[168:169], v[72:73], v[40:41]
	v_cmp_lt_u32_e64 s[44:45], s3, v212
	s_and_saveexec_b64 s[4:5], s[44:45]
	s_xor_b64 s[4:5], exec, s[4:5]
	v_ashrrev_i32_e32 v72, 10, v212
	v_cmp_lt_i32_e32 vcc, 1, v72
	s_mov_b64 s[36:37], 0
	s_mov_b64 s[54:55], 0
	s_and_saveexec_b64 s[56:57], vcc
	s_xor_b64 s[56:57], exec, s[56:57]
	v_cmp_ne_u32_e32 vcc, 2, v72
	s_and_b64 s[54:55], vcc, exec
	s_andn2_saveexec_b64 s[56:57], s[56:57]
	v_cmp_ne_u32_e32 vcc, 1, v72
	s_andn2_b64 s[36:37], s[54:55], exec
	s_and_b64 s[54:55], vcc, exec
	s_or_b64 s[54:55], s[36:37], s[54:55]
	s_mov_b64 s[36:37], exec
	s_or_b64 exec, exec, s[56:57]
	v_mov_b64_e32 v[172:173], v[168:169]
	v_mov_b64_e32 v[170:171], v[166:167]
	s_and_saveexec_b64 s[56:57], s[54:55]
	s_xor_b64 s[54:55], exec, s[56:57]
	s_or_b64 exec, exec, s[54:55]
	s_and_saveexec_b64 s[54:55], s[36:37]
	s_or_b64 exec, exec, s[54:55]
	s_andn2_saveexec_b64 s[4:5], s[4:5]
	s_or_b64 exec, exec, s[4:5]
	v_xor_b32_e32 v29, 0x80000000, v29
	v_xor_b32_e32 v28, 0x80000000, v28
	v_mov_b32_e32 v72, v200
	v_mov_b32_e32 v73, v200
	v_pk_fma_f32 v[162:163], v[26:27], v[200:201], v[162:163] neg_lo:[1,0,0] neg_hi:[1,0,0]
	v_pk_fma_f32 v[72:73], v[28:29], v[72:73], v[164:165]
	v_pk_fma_f32 v[162:163], v[192:193], v[162:163], v[22:23]
	v_mov_b32_e32 v193, v192
	v_pk_fma_f32 v[164:165], v[192:193], v[72:73], v[24:25]
	v_cvt_pk_bf16_f32 v166, v170, v171
	v_cvt_pk_bf16_f32 v167, v172, v173
	s_and_saveexec_b64 s[4:5], s[44:45]
	s_xor_b64 s[4:5], exec, s[4:5]
	v_ashrrev_i32_e32 v172, 10, v212
	v_cmp_lt_i32_e32 vcc, 1, v172
	s_mov_b64 s[36:37], 0
	s_mov_b64 s[54:55], 0
	s_and_saveexec_b64 s[56:57], vcc
	s_xor_b64 s[56:57], exec, s[56:57]
	v_cmp_ne_u32_e32 vcc, 2, v172
	s_and_b64 s[54:55], vcc, exec
	s_andn2_saveexec_b64 s[56:57], s[56:57]
	v_cmp_ne_u32_e32 vcc, 1, v172
	s_andn2_b64 s[36:37], s[54:55], exec
	s_and_b64 s[54:55], vcc, exec
	s_or_b64 s[54:55], s[36:37], s[54:55]
	s_mov_b64 s[36:37], exec
	s_or_b64 exec, exec, s[56:57]
	v_mov_b64_e32 v[170:171], v[164:165]
	v_mov_b64_e32 v[168:169], v[162:163]
	s_and_saveexec_b64 s[56:57], s[54:55]
	s_xor_b64 s[54:55], exec, s[56:57]
	s_or_b64 exec, exec, s[54:55]
	s_and_saveexec_b64 s[54:55], s[36:37]
	s_or_b64 exec, exec, s[54:55]
	s_andn2_saveexec_b64 s[4:5], s[4:5]
	s_or_b64 exec, exec, s[4:5]
	s_mov_b32 s3, 0x1020000
	v_cvt_pk_bf16_f32 v168, v168, v169
	v_cvt_pk_bf16_f32 v169, v170, v171
	v_mul_lo_u32 v170, v172, s3
	v_or_b32_e32 v72, v181, v203
	v_add_lshl_u32 v72, v72, v170, 1
	s_and_b64 vcc, exec, s[46:47]
	buffer_store_dwordx4 v[166:169], v72, s[28:31], 0 offen sc1
	s_cbranch_vccnz .LBB0_458_sg2
	ds_read_b64 v[166:167], v211 offset:128
	s_waitcnt lgkmcnt(0)
	v_mov_b32_e32 v72, v167
	s_branch .LBB0_459_sg2

.LBB0_408_sg3:
	s_waitcnt lgkmcnt(0)
	v_xor_b32_e32 v191, 0x80000000, v73
	v_xor_b32_e32 v190, 0x80000000, v72
	v_pk_fma_f32 v[72:73], v[190:191], v[200:201], v[176:177] op_sel_hi:[1,0,1]
	v_pk_fma_f32 v[174:175], v[70:71], v[200:201], v[174:175] op_sel_hi:[1,0,1] neg_lo:[1,0,0] neg_hi:[1,0,0]
	s_movk_i32 s4, 0x3ff
	v_pk_fma_f32 v[174:175], v[192:193], v[174:175], v[66:67] op_sel_hi:[0,1,1]
	v_pk_fma_f32 v[176:177], v[192:193], v[72:73], v[68:69] op_sel_hi:[0,1,1]
	v_cmp_lt_u32_e64 s[42:43], s4, v202
	s_and_saveexec_b64 s[4:5], s[42:43]
	s_xor_b64 s[4:5], exec, s[4:5]
	v_ashrrev_i32_e32 v72, 10, v202
	v_cmp_lt_i32_e32 vcc, 1, v72
	s_mov_b64 s[36:37], 0
	s_mov_b64 s[44:45], 0
	s_and_saveexec_b64 s[54:55], vcc
	s_xor_b64 s[54:55], exec, s[54:55]
	v_cmp_ne_u32_e32 vcc, 2, v72
	s_and_b64 s[44:45], vcc, exec
	s_andn2_saveexec_b64 s[54:55], s[54:55]
	v_cmp_ne_u32_e32 vcc, 1, v72
	s_andn2_b64 s[36:37], s[44:45], exec
	s_and_b64 s[44:45], vcc, exec
	s_or_b64 s[44:45], s[36:37], s[44:45]
	s_mov_b64 s[36:37], exec
	s_or_b64 exec, exec, s[54:55]
	v_mov_b64_e32 v[180:181], v[176:177]
	v_mov_b64_e32 v[178:179], v[174:175]
	s_and_saveexec_b64 s[54:55], s[44:45]
	s_xor_b64 s[44:45], exec, s[54:55]
	v_mul_f32_e32 v72, 0xbfb8aa3b, v174
	v_mul_f32_e32 v73, 0xbfb8aa3b, v175
	v_mul_f32_e32 v178, 0xbfb8aa3b, v176
	v_mul_f32_e32 v179, 0xbfb8aa3b, v177
	v_exp_f32_e32 v72, v72
	v_exp_f32_e32 v73, v73
	v_exp_f32_e32 v178, v178
	v_exp_f32_e32 v179, v179
	v_add_f32_e32 v72, 1.0, v72
	v_add_f32_e32 v73, 1.0, v73
	v_add_f32_e32 v178, 1.0, v178
	v_add_f32_e32 v179, 1.0, v179
	v_rcp_f32_e32 v72, v72
	v_rcp_f32_e32 v178, v178
	v_rcp_f32_e32 v179, v179
	v_rcp_f32_e32 v73, v73
	s_andn2_b64 s[36:37], s[36:37], exec
	v_pk_mul_f32 v[180:181], v[176:177], v[178:179]
	v_pk_mul_f32 v[178:179], v[174:175], v[72:73]
	s_or_b64 exec, exec, s[44:45]
	s_and_saveexec_b64 s[44:45], s[36:37]
	s_or_b64 exec, exec, s[44:45]
	s_andn2_saveexec_b64 s[4:5], s[4:5]
	s_or_b64 exec, exec, s[4:5]
	v_mov_b32_e32 v201, v200
	v_xor_b32_e32 v61, 0x80000000, v61
	v_xor_b32_e32 v60, 0x80000000, v60
	v_mov_b32_e32 v72, v200
	v_mov_b32_e32 v73, v200
	v_mov_b32_e32 v193, v192
	v_pk_fma_f32 v[72:73], v[60:61], v[72:73], v[172:173]
	v_pk_fma_f32 v[170:171], v[58:59], v[200:201], v[170:171] neg_lo:[1,0,0] neg_hi:[1,0,0]
	v_mov_b32_e32 v172, v192
	v_mov_b32_e32 v173, v192
	v_pk_fma_f32 v[170:171], v[192:193], v[170:171], v[54:55]
	v_pk_fma_f32 v[172:173], v[172:173], v[72:73], v[56:57]
	v_cvt_pk_bf16_f32 v174, v178, v179
	v_cvt_pk_bf16_f32 v175, v180, v181
	s_and_saveexec_b64 s[4:5], s[42:43]
	s_xor_b64 s[4:5], exec, s[4:5]
	v_ashrrev_i32_e32 v180, 10, v202
	v_cmp_lt_i32_e32 vcc, 1, v180
	s_mov_b64 s[36:37], 0
	s_mov_b64 s[44:45], 0
	s_and_saveexec_b64 s[54:55], vcc
	s_xor_b64 s[54:55], exec, s[54:55]
	v_cmp_ne_u32_e32 vcc, 2, v180
	s_and_b64 s[44:45], vcc, exec
	s_andn2_saveexec_b64 s[54:55], s[54:55]
	v_cmp_ne_u32_e32 vcc, 1, v180
	s_andn2_b64 s[36:37], s[44:45], exec
	s_and_b64 s[44:45], vcc, exec
	s_or_b64 s[44:45], s[36:37], s[44:45]
	s_mov_b64 s[36:37], exec
	s_or_b64 exec, exec, s[54:55]
	v_mov_b64_e32 v[178:179], v[172:173]
	v_mov_b64_e32 v[176:177], v[170:171]
	s_and_saveexec_b64 s[54:55], s[44:45]
	s_xor_b64 s[44:45], exec, s[54:55]
	v_mul_f32_e32 v72, 0xbfb8aa3b, v170
	v_mul_f32_e32 v73, 0xbfb8aa3b, v171
	v_mul_f32_e32 v176, 0xbfb8aa3b, v172
	v_mul_f32_e32 v177, 0xbfb8aa3b, v173
	v_exp_f32_e32 v72, v72
	v_exp_f32_e32 v73, v73
	v_exp_f32_e32 v176, v176
	v_exp_f32_e32 v177, v177
	v_add_f32_e32 v72, 1.0, v72
	v_add_f32_e32 v73, 1.0, v73
	v_add_f32_e32 v176, 1.0, v176
	v_add_f32_e32 v177, 1.0, v177
	v_rcp_f32_e32 v72, v72
	v_rcp_f32_e32 v176, v176
	v_rcp_f32_e32 v177, v177
	v_rcp_f32_e32 v73, v73
	s_andn2_b64 s[36:37], s[36:37], exec
	v_pk_mul_f32 v[178:179], v[172:173], v[176:177]
	v_pk_mul_f32 v[176:177], v[170:171], v[72:73]
	s_or_b64 exec, exec, s[44:45]
	s_and_saveexec_b64 s[44:45], s[36:37]
	s_or_b64 exec, exec, s[44:45]
	s_andn2_saveexec_b64 s[4:5], s[4:5]
	s_or_b64 exec, exec, s[4:5]
	s_lshl_b32 s51, s3, 8
	v_add_lshl_u32 v181, v214, s51, 10
	s_mov_b32 s3, 0x1020000
	v_cvt_pk_bf16_f32 v176, v176, v177
	v_cvt_pk_bf16_f32 v177, v178, v179
	v_mul_lo_u32 v178, v180, s3
	v_or_b32_e32 v72, v181, v210
	v_add_lshl_u32 v72, v72, v178, 1
	buffer_store_dwordx4 v[174:177], v72, s[28:31], 0 offen sc1
	v_xor_b32_e32 v45, 0x80000000, v45
	v_xor_b32_e32 v44, 0x80000000, v44
	v_mov_b32_e32 v72, v200
	v_mov_b32_e32 v73, v200
	v_pk_fma_f32 v[72:73], v[44:45], v[72:73], v[168:169]
	v_pk_fma_f32 v[166:167], v[42:43], v[200:201], v[166:167] neg_lo:[1,0,0] neg_hi:[1,0,0]
	v_mov_b32_e32 v168, v192
	v_mov_b32_e32 v169, v192
	s_movk_i32 s3, 0x3ff
	v_pk_fma_f32 v[166:167], v[192:193], v[166:167], v[38:39]
	v_pk_fma_f32 v[168:169], v[168:169], v[72:73], v[40:41]
	v_cmp_lt_u32_e64 s[44:45], s3, v212
	s_and_saveexec_b64 s[4:5], s[44:45]
	s_xor_b64 s[4:5], exec, s[4:5]
	v_ashrrev_i32_e32 v72, 10, v212
	v_cmp_lt_i32_e32 vcc, 1, v72
	s_mov_b64 s[36:37], 0
	s_mov_b64 s[54:55], 0
	s_and_saveexec_b64 s[56:57], vcc
	s_xor_b64 s[56:57], exec, s[56:57]
	v_cmp_ne_u32_e32 vcc, 2, v72
	s_and_b64 s[54:55], vcc, exec
	s_andn2_saveexec_b64 s[56:57], s[56:57]
	v_cmp_ne_u32_e32 vcc, 1, v72
	s_andn2_b64 s[36:37], s[54:55], exec
	s_and_b64 s[54:55], vcc, exec
	s_or_b64 s[54:55], s[36:37], s[54:55]
	s_mov_b64 s[36:37], exec
	s_or_b64 exec, exec, s[56:57]
	v_mov_b64_e32 v[172:173], v[168:169]
	v_mov_b64_e32 v[170:171], v[166:167]
	s_and_saveexec_b64 s[56:57], s[54:55]
	s_xor_b64 s[54:55], exec, s[56:57]
	v_mul_f32_e32 v72, 0xbfb8aa3b, v166
	v_mul_f32_e32 v73, 0xbfb8aa3b, v167
	v_mul_f32_e32 v170, 0xbfb8aa3b, v168
	v_mul_f32_e32 v171, 0xbfb8aa3b, v169
	v_exp_f32_e32 v72, v72
	v_exp_f32_e32 v73, v73
	v_exp_f32_e32 v170, v170
	v_exp_f32_e32 v171, v171
	v_add_f32_e32 v72, 1.0, v72
	v_add_f32_e32 v73, 1.0, v73
	v_add_f32_e32 v170, 1.0, v170
	v_add_f32_e32 v171, 1.0, v171
	v_rcp_f32_e32 v72, v72
	v_rcp_f32_e32 v170, v170
	v_rcp_f32_e32 v171, v171
	v_rcp_f32_e32 v73, v73
	s_andn2_b64 s[36:37], s[36:37], exec
	v_pk_mul_f32 v[172:173], v[168:169], v[170:171]
	v_pk_mul_f32 v[170:171], v[166:167], v[72:73]
	s_or_b64 exec, exec, s[54:55]
	s_and_saveexec_b64 s[54:55], s[36:37]
	s_or_b64 exec, exec, s[54:55]
	s_andn2_saveexec_b64 s[4:5], s[4:5]
	s_or_b64 exec, exec, s[4:5]
	v_xor_b32_e32 v29, 0x80000000, v29
	v_xor_b32_e32 v28, 0x80000000, v28
	v_mov_b32_e32 v72, v200
	v_mov_b32_e32 v73, v200
	v_pk_fma_f32 v[162:163], v[26:27], v[200:201], v[162:163] neg_lo:[1,0,0] neg_hi:[1,0,0]
	v_pk_fma_f32 v[72:73], v[28:29], v[72:73], v[164:165]
	v_pk_fma_f32 v[162:163], v[192:193], v[162:163], v[22:23]
	v_mov_b32_e32 v193, v192
	v_pk_fma_f32 v[164:165], v[192:193], v[72:73], v[24:25]
	v_cvt_pk_bf16_f32 v166, v170, v171
	v_cvt_pk_bf16_f32 v167, v172, v173
	s_and_saveexec_b64 s[4:5], s[44:45]
	s_xor_b64 s[4:5], exec, s[4:5]
	v_ashrrev_i32_e32 v172, 10, v212
	v_cmp_lt_i32_e32 vcc, 1, v172
	s_mov_b64 s[36:37], 0
	s_mov_b64 s[54:55], 0
	s_and_saveexec_b64 s[56:57], vcc
	s_xor_b64 s[56:57], exec, s[56:57]
	v_cmp_ne_u32_e32 vcc, 2, v172
	s_and_b64 s[54:55], vcc, exec
	s_andn2_saveexec_b64 s[56:57], s[56:57]
	v_cmp_ne_u32_e32 vcc, 1, v172
	s_andn2_b64 s[36:37], s[54:55], exec
	s_and_b64 s[54:55], vcc, exec
	s_or_b64 s[54:55], s[36:37], s[54:55]
	s_mov_b64 s[36:37], exec
	s_or_b64 exec, exec, s[56:57]
	v_mov_b64_e32 v[170:171], v[164:165]
	v_mov_b64_e32 v[168:169], v[162:163]
	s_and_saveexec_b64 s[56:57], s[54:55]
	s_xor_b64 s[54:55], exec, s[56:57]
	v_mul_f32_e32 v72, 0xbfb8aa3b, v162
	v_mul_f32_e32 v73, 0xbfb8aa3b, v163
	v_mul_f32_e32 v168, 0xbfb8aa3b, v164
	v_mul_f32_e32 v169, 0xbfb8aa3b, v165
	v_exp_f32_e32 v72, v72
	v_exp_f32_e32 v73, v73
	v_exp_f32_e32 v168, v168
	v_exp_f32_e32 v169, v169
	v_add_f32_e32 v72, 1.0, v72
	v_add_f32_e32 v73, 1.0, v73
	v_add_f32_e32 v168, 1.0, v168
	v_add_f32_e32 v169, 1.0, v169
	v_rcp_f32_e32 v72, v72
	v_rcp_f32_e32 v168, v168
	v_rcp_f32_e32 v169, v169
	v_rcp_f32_e32 v73, v73
	s_andn2_b64 s[36:37], s[36:37], exec
	v_pk_mul_f32 v[170:171], v[164:165], v[168:169]
	v_pk_mul_f32 v[168:169], v[162:163], v[72:73]
	s_or_b64 exec, exec, s[54:55]
	s_and_saveexec_b64 s[54:55], s[36:37]
	s_or_b64 exec, exec, s[54:55]
	s_andn2_saveexec_b64 s[4:5], s[4:5]
	s_or_b64 exec, exec, s[4:5]
	s_mov_b32 s3, 0x1020000
	v_cvt_pk_bf16_f32 v168, v168, v169
	v_cvt_pk_bf16_f32 v169, v170, v171
	v_mul_lo_u32 v170, v172, s3
	v_or_b32_e32 v72, v181, v203
	v_add_lshl_u32 v72, v72, v170, 1
	s_and_b64 vcc, exec, s[46:47]
	buffer_store_dwordx4 v[166:169], v72, s[28:31], 0 offen sc1
	s_cbranch_vccnz .LBB0_458_sg3
	ds_read_b64 v[166:167], v211 offset:128
	s_waitcnt lgkmcnt(0)
	v_mov_b32_e32 v72, v167
	s_branch .LBB0_459_sg3

	.amdhsa_kernel _Z19hgrn2_chunkmlp_mega6Params
		.amdhsa_group_segment_fixed_size 3072
		.amdhsa_private_segment_fixed_size 0
		.amdhsa_kernarg_size 424
		.amdhsa_user_sgpr_count 2
		.amdhsa_user_sgpr_dispatch_ptr 0
		.amdhsa_user_sgpr_queue_ptr 0
		.amdhsa_user_sgpr_kernarg_segment_ptr 1
		.amdhsa_user_sgpr_dispatch_id 0
		.amdhsa_user_sgpr_kernarg_preload_length 0
		.amdhsa_user_sgpr_kernarg_preload_offset 0
		.amdhsa_user_sgpr_private_segment_size 0
		.amdhsa_uses_dynamic_stack 0
		.amdhsa_enable_private_segment 0
		.amdhsa_system_sgpr_workgroup_id_x 1
		.amdhsa_system_sgpr_workgroup_id_y 0
		.amdhsa_system_sgpr_workgroup_id_z 0
		.amdhsa_system_sgpr_workgroup_info 0
		.amdhsa_system_vgpr_workitem_id 2
		.amdhsa_next_free_vgpr 256
		.amdhsa_next_free_sgpr 102
		.amdhsa_accum_offset 256
		.amdhsa_reserve_vcc 1
		.amdhsa_float_round_mode_32 0
		.amdhsa_float_round_mode_16_64 0
		.amdhsa_float_denorm_mode_32 3
		.amdhsa_float_denorm_mode_16_64 3
		.amdhsa_dx10_clamp 1
		.amdhsa_ieee_mode 1
		.amdhsa_fp16_overflow 0
		.amdhsa_tg_split 0
		.amdhsa_exception_fp_ieee_invalid_op 0
		.amdhsa_exception_fp_denorm_src 0
		.amdhsa_exception_fp_ieee_div_zero 0
		.amdhsa_exception_fp_ieee_overflow 0
		.amdhsa_exception_fp_ieee_underflow 0
		.amdhsa_exception_fp_ieee_inexact 0
		.amdhsa_exception_int_div_zero 0
	.end_amdhsa_kernel

amdhsa.kernels:
  - .agpr_count:     0
    .args:
      - .offset:         0
        .size:           168
        .value_kind:     by_value
      - .offset:         168
        .size:           4
        .value_kind:     hidden_block_count_x
      - .offset:         172
        .size:           4
        .value_kind:     hidden_block_count_y
      - .offset:         176
        .size:           4
        .value_kind:     hidden_block_count_z
      - .offset:         180
        .size:           2
        .value_kind:     hidden_group_size_x
      - .offset:         182
        .size:           2
        .value_kind:     hidden_group_size_y
      - .offset:         184
        .size:           2
        .value_kind:     hidden_group_size_z
      - .offset:         186
        .size:           2
        .value_kind:     hidden_remainder_x
      - .offset:         188
        .size:           2
        .value_kind:     hidden_remainder_y
      - .offset:         190
        .size:           2
        .value_kind:     hidden_remainder_z
      - .offset:         208
        .size:           8
        .value_kind:     hidden_global_offset_x
      - .offset:         216
        .size:           8
        .value_kind:     hidden_global_offset_y
      - .offset:         224
        .size:           8
        .value_kind:     hidden_global_offset_z
      - .offset:         232
        .size:           2
        .value_kind:     hidden_grid_dims
      - .offset:         256
        .size:           8
        .value_kind:     hidden_multigrid_sync_arg
      - .offset:         288
        .size:           4
        .value_kind:     hidden_dynamic_lds_size
    .group_segment_fixed_size: 3072
    .kernarg_segment_align: 8
    .kernarg_segment_size: 424
    .language:       OpenCL C
    .language_version:
      - 2
      - 0
    .max_flat_workgroup_size: 512
    .name:           _Z19hgrn2_chunkmlp_mega6Params
    .private_segment_fixed_size: 0
    .sgpr_count:     108
    .sgpr_spill_count: 245
    .symbol:         _Z19hgrn2_chunkmlp_mega6Params.kd
    .uniform_work_group_size: 1
    .uses_dynamic_stack: false
    .vgpr_count:     256
    .vgpr_spill_count: 0
    .wavefront_size: 64
